# natten loop: per-wave skip of score columns that are outside every query window of the wave (exact zeros), two loop variants
# speedup vs baseline: 1.0094x; 1.0069x over previous
; __device__ __forceinline__ unsigned cvtpk(float lo, float hi) { f32x2_t v = {lo, hi}; bf16x2_t b = __builtin_convertvector(v, bf16x2_t); return __builtin_bit_cast(unsigned, b); }
; #define A_BAR() asm volatile("s_waitcnt lgkmcnt(0)\n\ts_barrier" ::: "memory")
; __device__ __forceinline__ void attn_unit_A(const AttnP& P, int u, LAS char* lds) {
;     ...
;         float sacc = 0.f;
; #pragma unroll
;         for (int r = 0; r < 16; ++r) { sa0[r] = __builtin_amdgcn_exp2f(sa0[r]); sa1[r] = __builtin_amdgcn_exp2f(sa1[r]); sacc += sa0[r] + sa1[r]; }
;         lrun += sacc;
;         bf16x8 pf[4];
;         { u32x4 a;
;           a.x = cvtpk(sa0[0], sa0[1]); a.y = cvtpk(sa0[2], sa0[3]); a.z = cvtpk(sa0[4], sa0[5]); a.w = cvtpk(sa0[6], sa0[7]); pf[0] = __builtin_bit_cast(bf16x8, a);
;           a.x = cvtpk(sa0[8], sa0[9]); a.y = cvtpk(sa0[10], sa0[11]); a.z = cvtpk(sa0[12], sa0[13]); a.w = cvtpk(sa0[14], sa0[15]); pf[1] = __builtin_bit_cast(bf16x8, a);
;           a.x = cvtpk(sa1[0], sa1[1]); a.y = cvtpk(sa1[2], sa1[3]); a.z = cvtpk(sa1[4], sa1[5]); a.w = cvtpk(sa1[6], sa1[7]); pf[2] = __builtin_bit_cast(bf16x8, a);
;           a.x = cvtpk(sa1[8], sa1[9]); a.y = cvtpk(sa1[10], sa1[11]); a.z = cvtpk(sa1[12], sa1[13]); a.w = cvtpk(sa1[14], sa1[15]); pf[3] = __builtin_bit_cast(bf16x8, a); }
;         __builtin_amdgcn_sched_barrier(0);
;         A_VLOAD(vfb, 1);
;         __builtin_amdgcn_sched_barrier(0);
;         A_VMMA(vfa, 0);
;         A_VLOAD(vfa, 2);
;         __builtin_amdgcn_sched_barrier(0);
;         A_VMMA(vfb, 1);
;         A_VLOAD(vfb, 3);
;         __builtin_amdgcn_sched_barrier(0);
;         A_VMMA(vfa, 2);
;         __builtin_amdgcn_sched_barrier(0);
;         A_VMMA(vfb, 3);
;     ...
;         __builtin_amdgcn_sched_barrier(0); A_BAR(); A_QKBLK();
;     ...
;         if (more) {
;             if (clsn == 1) A_NEAR(sa0, sa1, t + 1);
;             float mx_; A_ROWMAX(sa0, sa1, mx_);
;             if (__any(mx_ > 8.0f)) { const float dl = fmaxf(mx_, 0.f); const float f_ = __builtin_amdgcn_exp2f(-dl); lrun *= f_;
; #pragma unroll
;                 for (int r = 0; r < 16; ++r) { sa0[r] -= dl; sa1[r] -= dl; negc[r] -= dl; }
; #pragma unroll
;                 for (int d = 0; d < 4; ++d)
; #pragma unroll
;                     for (int r = 0; r < 16; ++r) o[d][r] *= f_; }
;         }
;         bcur = bnext; bnext = bnext + ABUF; if (bnext == 3 * ABUF) bnext = 0;
.Latt1_e_join:
	s_waitcnt lgkmcnt(7)
	v_mfma_f32_32x32x16_bf16 v[96:111], v[222:225], v[136:139], v[96:111]
	ds_read_b64_tr_b16 v[222:223], v235 offset:18496
	ds_read_b64_tr_b16 v[224:225], v235 offset:20032
	v_add_f32_e32 v179, v179, v210
	v_add_f32_e32 v202, v202, v211
	v_add_f32_e32 v179, v179, v212
	v_add_f32_e32 v202, v202, v213
	v_exp_f32_e32 v214, v214
	s_waitcnt lgkmcnt(8)
	v_mfma_f32_32x32x16_bf16 v[112:127], v[226:229], v[136:139], v[112:127]
	ds_read_b64_tr_b16 v[226:227], v235 offset:30720
	ds_read_b64_tr_b16 v[228:229], v235 offset:32256
	v_cvt_pk_bf16_f32 v206, v206, v207
	v_cvt_pk_bf16_f32 v207, v208, v209
	v_cvt_pk_bf16_f32 v208, v210, v211
	v_cvt_pk_bf16_f32 v209, v212, v213
	v_exp_f32_e32 v215, v215
	s_waitcnt lgkmcnt(9)
	v_mfma_f32_32x32x16_bf16 v[96:111], v[230:233], v[132:135], v[96:111]
	ds_read_b64_tr_b16 v[230:231], v235 offset:30784
	ds_read_b64_tr_b16 v[232:233], v235 offset:32320
	v_exp_f32_e32 v216, v216
	v_exp_f32_e32 v217, v217
	v_exp_f32_e32 v218, v218
	s_waitcnt lgkmcnt(10)
	v_mfma_f32_32x32x16_bf16 v[112:127], v[244:247], v[132:135], v[112:127]
	ds_read_b64_tr_b16 v[244:245], v235 offset:21504
	ds_read_b64_tr_b16 v[246:247], v235 offset:23040
	v_exp_f32_e32 v219, v219
	v_exp_f32_e32 v220, v220
	v_exp_f32_e32 v221, v221
	s_waitcnt lgkmcnt(11)
	v_mfma_f32_32x32x16_bf16 v[96:111], v[248:251], v[128:131], v[96:111]
	ds_read_b64_tr_b16 v[248:249], v235 offset:21568
	ds_read_b64_tr_b16 v[250:251], v235 offset:23104
	v_add_f32_e32 v179, v179, v214
	v_add_f32_e32 v202, v202, v215
	v_add_f32_e32 v179, v179, v216
	v_add_f32_e32 v202, v202, v217
	v_add_f32_e32 v179, v179, v218
	v_add_f32_e32 v202, v202, v219
	s_waitcnt lgkmcnt(12)
	v_mfma_f32_32x32x16_bf16 v[112:127], v[184:187], v[128:131], v[112:127]
	ds_read_b64_tr_b16 v[184:185], v235 offset:33792
	ds_read_b64_tr_b16 v[186:187], v235 offset:35328
	v_add_f32_e32 v179, v179, v220
	v_add_f32_e32 v202, v202, v221
	v_cvt_pk_bf16_f32 v210, v214, v215
	v_cvt_pk_bf16_f32 v211, v216, v217
	v_cvt_pk_bf16_f32 v212, v218, v219
	v_cvt_pk_bf16_f32 v213, v220, v221
	s_waitcnt lgkmcnt(12)
	v_mfma_f32_32x32x16_bf16 v[64:79], v[188:191], v[206:209], v[64:79]
	ds_read_b64_tr_b16 v[188:189], v235 offset:33856
	ds_read_b64_tr_b16 v[190:191], v235 offset:35392
	v_exp_f32_e32 v0, v0
	v_exp_f32_e32 v1, v1
	v_exp_f32_e32 v2, v2
	s_waitcnt lgkmcnt(12)
	v_mfma_f32_32x32x16_bf16 v[48:63], v[222:225], v[206:209], v[48:63]
	ds_read_b64_tr_b16 v[222:223], v235 offset:24576
	ds_read_b64_tr_b16 v[224:225], v235 offset:26112
	v_exp_f32_e32 v3, v3
	v_exp_f32_e32 v4, v4
	v_exp_f32_e32 v5, v5
	s_waitcnt lgkmcnt(12)
	v_mfma_f32_32x32x16_bf16 v[32:47], v[226:229], v[206:209], v[32:47]
	ds_read_b64_tr_b16 v[226:227], v235 offset:24640
	ds_read_b64_tr_b16 v[228:229], v235 offset:26176
	v_exp_f32_e32 v6, v6
	v_exp_f32_e32 v7, v7
	v_add_f32_e32 v179, v179, v0
	v_add_f32_e32 v202, v202, v1
	s_waitcnt lgkmcnt(12)
	v_mfma_f32_32x32x16_bf16 v[16:31], v[230:233], v[206:209], v[16:31]
	ds_read_b64_tr_b16 v[230:231], v235 offset:36864
	ds_read_b64_tr_b16 v[232:233], v235 offset:38400
	v_add_f32_e32 v179, v179, v2
	v_add_f32_e32 v202, v202, v3
	v_add_f32_e32 v179, v179, v4
	v_add_f32_e32 v202, v202, v5
	v_add_f32_e32 v179, v179, v6
	v_add_f32_e32 v202, v202, v7
	s_waitcnt lgkmcnt(12)
	v_mfma_f32_32x32x16_bf16 v[64:79], v[244:247], v[210:213], v[64:79]
	ds_read_b64_tr_b16 v[244:245], v235 offset:36928
	ds_read_b64_tr_b16 v[246:247], v235 offset:38464
	v_cvt_pk_bf16_f32 v214, v0, v1
	v_cvt_pk_bf16_f32 v215, v2, v3
	v_cvt_pk_bf16_f32 v216, v4, v5
	v_cvt_pk_bf16_f32 v217, v6, v7
	v_exp_f32_e32 v8, v8
	s_waitcnt lgkmcnt(12)
	v_mfma_f32_32x32x16_bf16 v[48:63], v[248:251], v[210:213], v[48:63]
	ds_read_b64_tr_b16 v[248:249], v235 offset:27648
	ds_read_b64_tr_b16 v[250:251], v235 offset:29184
	v_exp_f32_e32 v9, v9
	v_exp_f32_e32 v10, v10
	v_exp_f32_e32 v11, v11
	s_waitcnt lgkmcnt(12)
	v_mfma_f32_32x32x16_bf16 v[32:47], v[184:187], v[210:213], v[32:47]
	ds_read_b64_tr_b16 v[184:185], v235 offset:27712
	ds_read_b64_tr_b16 v[186:187], v235 offset:29248
	v_exp_f32_e32 v12, v12
	v_exp_f32_e32 v13, v13
	v_exp_f32_e32 v14, v14
	s_waitcnt lgkmcnt(12)
	v_mfma_f32_32x32x16_bf16 v[16:31], v[188:191], v[210:213], v[16:31]
	ds_read_b64_tr_b16 v[188:189], v235 offset:39936
	ds_read_b64_tr_b16 v[190:191], v235 offset:41472
	v_exp_f32_e32 v15, v15
	v_add_f32_e32 v179, v179, v8
	v_add_f32_e32 v202, v202, v9
	v_add_f32_e32 v179, v179, v10
	v_add_f32_e32 v202, v202, v11
	s_waitcnt lgkmcnt(12)
	v_mfma_f32_32x32x16_bf16 v[64:79], v[222:225], v[214:217], v[64:79]
	ds_read_b64_tr_b16 v[222:223], v235 offset:40000
	ds_read_b64_tr_b16 v[224:225], v235 offset:41536
	v_add_f32_e32 v179, v179, v12
	v_add_f32_e32 v202, v202, v13
	v_add_f32_e32 v179, v179, v14
	v_add_f32_e32 v202, v202, v15
	v_max3_f32 v243, v96, v97, v98
	v_max3_f32 v239, v112, v113, v114
	s_waitcnt lgkmcnt(12)
	v_mfma_f32_32x32x16_bf16 v[48:63], v[226:229], v[214:217], v[48:63]
	v_cvt_pk_bf16_f32 v218, v8, v9
	v_cvt_pk_bf16_f32 v219, v10, v11
	v_cvt_pk_bf16_f32 v220, v12, v13
	v_cvt_pk_bf16_f32 v221, v14, v15
	v_max3_f32 v243, v243, v99, v100
	v_max3_f32 v239, v239, v115, v116
	v_max3_f32 v243, v243, v101, v102
	v_max3_f32 v239, v239, v117, v118
	s_waitcnt lgkmcnt(10)
; __device__ __forceinline__ unsigned cvtpk(float lo, float hi) { f32x2_t v = {lo, hi}; bf16x2_t b = __builtin_convertvector(v, bf16x2_t); return __builtin_bit_cast(unsigned, b); }
; #define A_BAR() asm volatile("s_waitcnt lgkmcnt(0)\n\ts_barrier" ::: "memory")
; __device__ __forceinline__ void attn_unit_A(const AttnP& P, int u, LAS char* lds) {
;     ...
;         float sacc = 0.f;
; #pragma unroll
;         for (int r = 0; r < 16; ++r) { sa0[r] = __builtin_amdgcn_exp2f(sa0[r]); sa1[r] = __builtin_amdgcn_exp2f(sa1[r]); sacc += sa0[r] + sa1[r]; }
;         lrun += sacc;
;         bf16x8 pf[4];
;         { u32x4 a;
;           a.x = cvtpk(sa0[0], sa0[1]); a.y = cvtpk(sa0[2], sa0[3]); a.z = cvtpk(sa0[4], sa0[5]); a.w = cvtpk(sa0[6], sa0[7]); pf[0] = __builtin_bit_cast(bf16x8, a);
;           a.x = cvtpk(sa0[8], sa0[9]); a.y = cvtpk(sa0[10], sa0[11]); a.z = cvtpk(sa0[12], sa0[13]); a.w = cvtpk(sa0[14], sa0[15]); pf[1] = __builtin_bit_cast(bf16x8, a);
;           a.x = cvtpk(sa1[0], sa1[1]); a.y = cvtpk(sa1[2], sa1[3]); a.z = cvtpk(sa1[4], sa1[5]); a.w = cvtpk(sa1[6], sa1[7]); pf[2] = __builtin_bit_cast(bf16x8, a);
;           a.x = cvtpk(sa1[8], sa1[9]); a.y = cvtpk(sa1[10], sa1[11]); a.z = cvtpk(sa1[12], sa1[13]); a.w = cvtpk(sa1[14], sa1[15]); pf[3] = __builtin_bit_cast(bf16x8, a); }
;         __builtin_amdgcn_sched_barrier(0);
;         A_VLOAD(vfb, 1);
;         __builtin_amdgcn_sched_barrier(0);
;         A_VMMA(vfa, 0);
;         A_VLOAD(vfa, 2);
;         __builtin_amdgcn_sched_barrier(0);
;         A_VMMA(vfb, 1);
;         A_VLOAD(vfb, 3);
;         __builtin_amdgcn_sched_barrier(0);
;         A_VMMA(vfa, 2);
;         __builtin_amdgcn_sched_barrier(0);
;         A_VMMA(vfb, 3);
;     ...
;         __builtin_amdgcn_sched_barrier(0); A_BAR(); A_QKBLK();
;     ...
;         if (more) {
;             if (clsn == 1) A_NEAR(sa0, sa1, t + 1);
;             float mx_; A_ROWMAX(sa0, sa1, mx_);
;             if (__any(mx_ > 8.0f)) { const float dl = fmaxf(mx_, 0.f); const float f_ = __builtin_amdgcn_exp2f(-dl); lrun *= f_;
; #pragma unroll
;                 for (int r = 0; r < 16; ++r) { sa0[r] -= dl; sa1[r] -= dl; negc[r] -= dl; }
; #pragma unroll
;                 for (int d = 0; d < 4; ++d)
; #pragma unroll
;                     for (int r = 0; r < 16; ++r) o[d][r] *= f_; }
;         }
;         bcur = bnext; bnext = bnext + ABUF; if (bnext == 3 * ABUF) bnext = 0;
	v_mfma_f32_32x32x16_bf16 v[32:47], v[230:233], v[214:217], v[32:47]
	v_max3_f32 v243, v243, v103, v104
	v_max3_f32 v239, v239, v119, v120
	v_max3_f32 v243, v243, v105, v106
	v_max3_f32 v239, v239, v121, v122
	v_max3_f32 v243, v243, v107, v108
	v_max3_f32 v239, v239, v123, v124
	v_max3_f32 v243, v243, v109, v110
	v_max3_f32 v239, v239, v125, v126
	v_max_f32_e32 v243, v243, v111
	v_max_f32_e32 v239, v239, v127
	v_max_f32_e32 v243, v243, v239
	s_waitcnt lgkmcnt(8)
	v_mfma_f32_32x32x16_bf16 v[16:31], v[244:247], v[214:217], v[16:31]
	s_waitcnt vmcnt(0)
	v_add3_u32 v238, s38, v178, v160
	v_add3_u32 v239, s38, v180, v160
	ds_write_b128 v238, v[156:159]
	ds_write_b128 v238, v[152:155] offset:9216
	s_waitcnt lgkmcnt(8)
	v_mfma_f32_32x32x16_bf16 v[64:79], v[248:251], v[218:221], v[64:79]
	ds_write_b128 v239, v[148:151] offset:18432
	ds_write_b128 v239, v[144:147] offset:30720
	v_mov_b32_e32 v239, v243
	s_min_i32 s0, s31, 0xf80
	v_add_u32_e32 v238, s0, v181
	v_min_i32_e32 v238, 0x100f, v238
	s_waitcnt lgkmcnt(8)
	v_mfma_f32_32x32x16_bf16 v[48:63], v[184:187], v[218:221], v[48:63]
	v_permlane32_swap_b32_e32 v243, v239
	v_mad_i64_i32 v[192:193], s[0:1], v238, s51, v[162:163]
	global_load_dwordx4 v[156:159], v[192:193], off offset:1024
	global_load_dwordx4 v[152:155], v[192:193], off offset:1152
	s_waitcnt lgkmcnt(6)
	v_mfma_f32_32x32x16_bf16 v[32:47], v[188:191], v[218:221], v[32:47]
	global_load_dwordx4 v[148:151], v[192:193], off offset:2048
	global_load_dwordx4 v[144:147], v[192:193], off offset:2176
	v_max_f32_e32 v243, v243, v239
	s_waitcnt lgkmcnt(4)
	v_mfma_f32_32x32x16_bf16 v[16:31], v[222:225], v[218:221], v[16:31]
	s_mov_b32 s39, s30
	s_mov_b32 s26, s29
	s_mov_b32 s29, s38
	s_add_i32 s0, s38, 0xa800
	s_cmp_lg_u32 s0, 0x1f800
	s_cselect_b32 s38, s0, 0
	s_mov_b32 s35, s31
	v_cmp_lt_f32_e32 vcc, s10, v243
	s_cbranch_vccz .Latt1_e_noresc
	s_nop 11
	v_max_f32_e32 v243, 0, v243
	v_exp_f32_e64 v192, -v243
	v_sub_f32_e32 v80, v80, v243
	v_sub_f32_e32 v81, v81, v243
	v_sub_f32_e32 v82, v82, v243
	v_sub_f32_e32 v83, v83, v243
	v_sub_f32_e32 v84, v84, v243
	v_sub_f32_e32 v85, v85, v243
	v_sub_f32_e32 v86, v86, v243
	v_sub_f32_e32 v87, v87, v243
	v_sub_f32_e32 v88, v88, v243
	v_sub_f32_e32 v89, v89, v243
	v_sub_f32_e32 v90, v90, v243
	v_sub_f32_e32 v91, v91, v243
	v_sub_f32_e32 v92, v92, v243
	v_sub_f32_e32 v93, v93, v243
	v_sub_f32_e32 v94, v94, v243
	v_sub_f32_e32 v95, v95, v243
	v_sub_f32_e32 v96, v96, v243
	v_sub_f32_e32 v97, v97, v243
	v_sub_f32_e32 v98, v98, v243
	v_sub_f32_e32 v99, v99, v243
	v_sub_f32_e32 v100, v100, v243
	v_sub_f32_e32 v101, v101, v243
	v_sub_f32_e32 v102, v102, v243
	v_sub_f32_e32 v103, v103, v243
	v_sub_f32_e32 v104, v104, v243
	v_sub_f32_e32 v105, v105, v243
	v_sub_f32_e32 v106, v106, v243
	v_sub_f32_e32 v107, v107, v243
	v_sub_f32_e32 v108, v108, v243
	v_sub_f32_e32 v109, v109, v243
	v_sub_f32_e32 v110, v110, v243
	v_sub_f32_e32 v111, v111, v243
	v_sub_f32_e32 v112, v112, v243
	v_sub_f32_e32 v113, v113, v243
	v_sub_f32_e32 v114, v114, v243
	v_sub_f32_e32 v115, v115, v243
	v_sub_f32_e32 v116, v116, v243
	v_sub_f32_e32 v117, v117, v243
	v_sub_f32_e32 v118, v118, v243
	v_sub_f32_e32 v119, v119, v243
	v_sub_f32_e32 v120, v120, v243
	v_sub_f32_e32 v121, v121, v243
	v_sub_f32_e32 v122, v122, v243
	v_sub_f32_e32 v123, v123, v243
	v_sub_f32_e32 v124, v124, v243
	v_sub_f32_e32 v125, v125, v243
	v_sub_f32_e32 v126, v126, v243
	v_sub_f32_e32 v127, v127, v243
	v_pk_mul_f32 v[64:65], v[64:65], v[192:193] op_sel_hi:[1,0]
	v_pk_mul_f32 v[66:67], v[66:67], v[192:193] op_sel_hi:[1,0]
	v_pk_mul_f32 v[68:69], v[68:69], v[192:193] op_sel_hi:[1,0]
	v_pk_mul_f32 v[70:71], v[70:71], v[192:193] op_sel_hi:[1,0]
	v_pk_mul_f32 v[72:73], v[72:73], v[192:193] op_sel_hi:[1,0]
	v_pk_mul_f32 v[74:75], v[74:75], v[192:193] op_sel_hi:[1,0]
	v_pk_mul_f32 v[76:77], v[76:77], v[192:193] op_sel_hi:[1,0]
	v_pk_mul_f32 v[78:79], v[78:79], v[192:193] op_sel_hi:[1,0]
	v_pk_mul_f32 v[48:49], v[48:49], v[192:193] op_sel_hi:[1,0]
	v_pk_mul_f32 v[50:51], v[50:51], v[192:193] op_sel_hi:[1,0]
	v_pk_mul_f32 v[52:53], v[52:53], v[192:193] op_sel_hi:[1,0]
	v_pk_mul_f32 v[54:55], v[54:55], v[192:193] op_sel_hi:[1,0]
	v_pk_mul_f32 v[56:57], v[56:57], v[192:193] op_sel_hi:[1,0]
	v_pk_mul_f32 v[58:59], v[58:59], v[192:193] op_sel_hi:[1,0]
	v_pk_mul_f32 v[60:61], v[60:61], v[192:193] op_sel_hi:[1,0]
	v_pk_mul_f32 v[62:63], v[62:63], v[192:193] op_sel_hi:[1,0]
	v_pk_mul_f32 v[32:33], v[32:33], v[192:193] op_sel_hi:[1,0]
	v_pk_mul_f32 v[34:35], v[34:35], v[192:193] op_sel_hi:[1,0]
	v_pk_mul_f32 v[36:37], v[36:37], v[192:193] op_sel_hi:[1,0]
	v_pk_mul_f32 v[38:39], v[38:39], v[192:193] op_sel_hi:[1,0]
	v_pk_mul_f32 v[40:41], v[40:41], v[192:193] op_sel_hi:[1,0]
	v_pk_mul_f32 v[42:43], v[42:43], v[192:193] op_sel_hi:[1,0]
	v_pk_mul_f32 v[44:45], v[44:45], v[192:193] op_sel_hi:[1,0]
	v_pk_mul_f32 v[46:47], v[46:47], v[192:193] op_sel_hi:[1,0]
	v_pk_mul_f32 v[16:17], v[16:17], v[192:193] op_sel_hi:[1,0]
	v_pk_mul_f32 v[18:19], v[18:19], v[192:193] op_sel_hi:[1,0]
	v_pk_mul_f32 v[20:21], v[20:21], v[192:193] op_sel_hi:[1,0]
	v_pk_mul_f32 v[22:23], v[22:23], v[192:193] op_sel_hi:[1,0]
	v_pk_mul_f32 v[24:25], v[24:25], v[192:193] op_sel_hi:[1,0]
	v_pk_mul_f32 v[26:27], v[26:27], v[192:193] op_sel_hi:[1,0]
	v_pk_mul_f32 v[28:29], v[28:29], v[192:193] op_sel_hi:[1,0]
	v_pk_mul_f32 v[30:31], v[30:31], v[192:193] op_sel_hi:[1,0]
	v_mul_f32_e32 v179, v179, v192
	v_mul_f32_e32 v202, v202, v192
	s_nop 1

; __device__ __forceinline__ unsigned cvtpk(float lo, float hi) { f32x2_t v = {lo, hi}; bf16x2_t b = __builtin_convertvector(v, bf16x2_t); return __builtin_bit_cast(unsigned, b); }
; #define A_BAR() asm volatile("s_waitcnt lgkmcnt(0)\n\ts_barrier" ::: "memory")
; __device__ __forceinline__ void attn_unit_A(const AttnP& P, int u, LAS char* lds) {
;     ...
;         float sacc = 0.f;
; #pragma unroll
;         for (int r = 0; r < 16; ++r) { sa0[r] = __builtin_amdgcn_exp2f(sa0[r]); sa1[r] = __builtin_amdgcn_exp2f(sa1[r]); sacc += sa0[r] + sa1[r]; }
;         lrun += sacc;
;         bf16x8 pf[4];
;         { u32x4 a;
;           a.x = cvtpk(sa0[0], sa0[1]); a.y = cvtpk(sa0[2], sa0[3]); a.z = cvtpk(sa0[4], sa0[5]); a.w = cvtpk(sa0[6], sa0[7]); pf[0] = __builtin_bit_cast(bf16x8, a);
;           a.x = cvtpk(sa0[8], sa0[9]); a.y = cvtpk(sa0[10], sa0[11]); a.z = cvtpk(sa0[12], sa0[13]); a.w = cvtpk(sa0[14], sa0[15]); pf[1] = __builtin_bit_cast(bf16x8, a);
;           a.x = cvtpk(sa1[0], sa1[1]); a.y = cvtpk(sa1[2], sa1[3]); a.z = cvtpk(sa1[4], sa1[5]); a.w = cvtpk(sa1[6], sa1[7]); pf[2] = __builtin_bit_cast(bf16x8, a);
;           a.x = cvtpk(sa1[8], sa1[9]); a.y = cvtpk(sa1[10], sa1[11]); a.z = cvtpk(sa1[12], sa1[13]); a.w = cvtpk(sa1[14], sa1[15]); pf[3] = __builtin_bit_cast(bf16x8, a); }
;         __builtin_amdgcn_sched_barrier(0);
;         A_VLOAD(vfb, 1);
;         __builtin_amdgcn_sched_barrier(0);
;         A_VMMA(vfa, 0);
;         A_VLOAD(vfa, 2);
;         __builtin_amdgcn_sched_barrier(0);
;         A_VMMA(vfb, 1);
;         A_VLOAD(vfb, 3);
;         __builtin_amdgcn_sched_barrier(0);
;         A_VMMA(vfa, 2);
;         __builtin_amdgcn_sched_barrier(0);
;         A_VMMA(vfb, 3);
;     ...
;         __builtin_amdgcn_sched_barrier(0); A_BAR(); A_QKBLK();
;     ...
;         if (more) {
;             if (clsn == 1) A_NEAR(sa0, sa1, t + 1);
;             float mx_; A_ROWMAX(sa0, sa1, mx_);
;             if (__any(mx_ > 8.0f)) { const float dl = fmaxf(mx_, 0.f); const float f_ = __builtin_amdgcn_exp2f(-dl); lrun *= f_;
; #pragma unroll
;                 for (int r = 0; r < 16; ++r) { sa0[r] -= dl; sa1[r] -= dl; negc[r] -= dl; }
; #pragma unroll
;                 for (int d = 0; d < 4; ++d)
; #pragma unroll
;                     for (int r = 0; r < 16; ++r) o[d][r] *= f_; }
;         }
;         bcur = bnext; bnext = bnext + ABUF; if (bnext == 3 * ABUF) bnext = 0;
.Latt1_o_join:
	s_waitcnt lgkmcnt(7)
	v_mfma_f32_32x32x16_bf16 v[206:221], v[222:225], v[136:139], v[206:221]
	ds_read_b64_tr_b16 v[222:223], v235 offset:18496
	ds_read_b64_tr_b16 v[224:225], v235 offset:20032
	v_add_f32_e32 v179, v179, v100
	v_add_f32_e32 v202, v202, v101
	v_add_f32_e32 v179, v179, v102
	v_add_f32_e32 v202, v202, v103
	v_exp_f32_e32 v104, v104
	s_waitcnt lgkmcnt(8)
	v_mfma_f32_32x32x16_bf16 v[0:15], v[226:229], v[136:139], v[0:15]
	ds_read_b64_tr_b16 v[226:227], v235 offset:30720
	ds_read_b64_tr_b16 v[228:229], v235 offset:32256
	v_cvt_pk_bf16_f32 v96, v96, v97
	v_cvt_pk_bf16_f32 v97, v98, v99
	v_cvt_pk_bf16_f32 v98, v100, v101
	v_cvt_pk_bf16_f32 v99, v102, v103
	v_exp_f32_e32 v105, v105
	s_waitcnt lgkmcnt(9)
	v_mfma_f32_32x32x16_bf16 v[206:221], v[230:233], v[132:135], v[206:221]
	ds_read_b64_tr_b16 v[230:231], v235 offset:30784
	ds_read_b64_tr_b16 v[232:233], v235 offset:32320
	v_exp_f32_e32 v106, v106
	v_exp_f32_e32 v107, v107
	v_exp_f32_e32 v108, v108
	s_waitcnt lgkmcnt(10)
	v_mfma_f32_32x32x16_bf16 v[0:15], v[244:247], v[132:135], v[0:15]
	ds_read_b64_tr_b16 v[244:245], v235 offset:21504
	ds_read_b64_tr_b16 v[246:247], v235 offset:23040
	v_exp_f32_e32 v109, v109
	v_exp_f32_e32 v110, v110
	v_exp_f32_e32 v111, v111
	s_waitcnt lgkmcnt(11)
	v_mfma_f32_32x32x16_bf16 v[206:221], v[248:251], v[128:131], v[206:221]
	ds_read_b64_tr_b16 v[248:249], v235 offset:21568
	ds_read_b64_tr_b16 v[250:251], v235 offset:23104
	v_add_f32_e32 v179, v179, v104
	v_add_f32_e32 v202, v202, v105
	v_add_f32_e32 v179, v179, v106
	v_add_f32_e32 v202, v202, v107
	v_add_f32_e32 v179, v179, v108
	v_add_f32_e32 v202, v202, v109
	s_waitcnt lgkmcnt(12)
	v_mfma_f32_32x32x16_bf16 v[0:15], v[184:187], v[128:131], v[0:15]
	ds_read_b64_tr_b16 v[184:185], v235 offset:33792
	ds_read_b64_tr_b16 v[186:187], v235 offset:35328
	v_add_f32_e32 v179, v179, v110
	v_add_f32_e32 v202, v202, v111
	v_cvt_pk_bf16_f32 v100, v104, v105
	v_cvt_pk_bf16_f32 v101, v106, v107
	v_cvt_pk_bf16_f32 v102, v108, v109
	v_cvt_pk_bf16_f32 v103, v110, v111
	s_waitcnt lgkmcnt(12)
	v_mfma_f32_32x32x16_bf16 v[64:79], v[188:191], v[96:99], v[64:79]
	ds_read_b64_tr_b16 v[188:189], v235 offset:33856
	ds_read_b64_tr_b16 v[190:191], v235 offset:35392
	v_exp_f32_e32 v112, v112
	v_exp_f32_e32 v113, v113
	v_exp_f32_e32 v114, v114
	s_waitcnt lgkmcnt(12)
	v_mfma_f32_32x32x16_bf16 v[48:63], v[222:225], v[96:99], v[48:63]
	ds_read_b64_tr_b16 v[222:223], v235 offset:24576
	ds_read_b64_tr_b16 v[224:225], v235 offset:26112
	v_exp_f32_e32 v115, v115
	v_exp_f32_e32 v116, v116
	v_exp_f32_e32 v117, v117
	s_waitcnt lgkmcnt(12)
	v_mfma_f32_32x32x16_bf16 v[32:47], v[226:229], v[96:99], v[32:47]
	ds_read_b64_tr_b16 v[226:227], v235 offset:24640
	ds_read_b64_tr_b16 v[228:229], v235 offset:26176
	v_exp_f32_e32 v118, v118
	v_exp_f32_e32 v119, v119
	v_add_f32_e32 v179, v179, v112
	v_add_f32_e32 v202, v202, v113
	s_waitcnt lgkmcnt(12)
	v_mfma_f32_32x32x16_bf16 v[16:31], v[230:233], v[96:99], v[16:31]
	ds_read_b64_tr_b16 v[230:231], v235 offset:36864
	ds_read_b64_tr_b16 v[232:233], v235 offset:38400
	v_add_f32_e32 v179, v179, v114
	v_add_f32_e32 v202, v202, v115
	v_add_f32_e32 v179, v179, v116
	v_add_f32_e32 v202, v202, v117
	v_add_f32_e32 v179, v179, v118
	v_add_f32_e32 v202, v202, v119
	s_waitcnt lgkmcnt(12)
	v_mfma_f32_32x32x16_bf16 v[64:79], v[244:247], v[100:103], v[64:79]
	ds_read_b64_tr_b16 v[244:245], v235 offset:36928
	ds_read_b64_tr_b16 v[246:247], v235 offset:38464
	v_cvt_pk_bf16_f32 v104, v112, v113
	v_cvt_pk_bf16_f32 v105, v114, v115
	v_cvt_pk_bf16_f32 v106, v116, v117
	v_cvt_pk_bf16_f32 v107, v118, v119
	v_exp_f32_e32 v120, v120
	s_waitcnt lgkmcnt(12)
	v_mfma_f32_32x32x16_bf16 v[48:63], v[248:251], v[100:103], v[48:63]
	ds_read_b64_tr_b16 v[248:249], v235 offset:27648
	ds_read_b64_tr_b16 v[250:251], v235 offset:29184
	v_exp_f32_e32 v121, v121
	v_exp_f32_e32 v122, v122
	v_exp_f32_e32 v123, v123
	s_waitcnt lgkmcnt(12)
	v_mfma_f32_32x32x16_bf16 v[32:47], v[184:187], v[100:103], v[32:47]
	ds_read_b64_tr_b16 v[184:185], v235 offset:27712
	ds_read_b64_tr_b16 v[186:187], v235 offset:29248
	v_exp_f32_e32 v124, v124
	v_exp_f32_e32 v125, v125
	v_exp_f32_e32 v126, v126
	s_waitcnt lgkmcnt(12)
	v_mfma_f32_32x32x16_bf16 v[16:31], v[188:191], v[100:103], v[16:31]
	ds_read_b64_tr_b16 v[188:189], v235 offset:39936
	ds_read_b64_tr_b16 v[190:191], v235 offset:41472
	v_exp_f32_e32 v127, v127
	v_add_f32_e32 v179, v179, v120
	v_add_f32_e32 v202, v202, v121
	v_add_f32_e32 v179, v179, v122
	v_add_f32_e32 v202, v202, v123
	s_waitcnt lgkmcnt(12)
	v_mfma_f32_32x32x16_bf16 v[64:79], v[222:225], v[104:107], v[64:79]
	ds_read_b64_tr_b16 v[222:223], v235 offset:40000
	ds_read_b64_tr_b16 v[224:225], v235 offset:41536
	v_add_f32_e32 v179, v179, v124
	v_add_f32_e32 v202, v202, v125
	v_add_f32_e32 v179, v179, v126
	v_add_f32_e32 v202, v202, v127
	v_max3_f32 v243, v206, v207, v208
	v_max3_f32 v239, v0, v1, v2
	s_waitcnt lgkmcnt(12)
	v_mfma_f32_32x32x16_bf16 v[48:63], v[226:229], v[104:107], v[48:63]
	v_cvt_pk_bf16_f32 v108, v120, v121
	v_cvt_pk_bf16_f32 v109, v122, v123
	v_cvt_pk_bf16_f32 v110, v124, v125
	v_cvt_pk_bf16_f32 v111, v126, v127
	v_max3_f32 v243, v243, v209, v210
	v_max3_f32 v239, v239, v3, v4
	v_max3_f32 v243, v243, v211, v212
	v_max3_f32 v239, v239, v5, v6
	s_waitcnt lgkmcnt(10)
; __device__ __forceinline__ unsigned cvtpk(float lo, float hi) { f32x2_t v = {lo, hi}; bf16x2_t b = __builtin_convertvector(v, bf16x2_t); return __builtin_bit_cast(unsigned, b); }
; #define A_BAR() asm volatile("s_waitcnt lgkmcnt(0)\n\ts_barrier" ::: "memory")
; __device__ __forceinline__ void attn_unit_A(const AttnP& P, int u, LAS char* lds) {
;     ...
;         float sacc = 0.f;
; #pragma unroll
;         for (int r = 0; r < 16; ++r) { sa0[r] = __builtin_amdgcn_exp2f(sa0[r]); sa1[r] = __builtin_amdgcn_exp2f(sa1[r]); sacc += sa0[r] + sa1[r]; }
;         lrun += sacc;
;         bf16x8 pf[4];
;         { u32x4 a;
;           a.x = cvtpk(sa0[0], sa0[1]); a.y = cvtpk(sa0[2], sa0[3]); a.z = cvtpk(sa0[4], sa0[5]); a.w = cvtpk(sa0[6], sa0[7]); pf[0] = __builtin_bit_cast(bf16x8, a);
;           a.x = cvtpk(sa0[8], sa0[9]); a.y = cvtpk(sa0[10], sa0[11]); a.z = cvtpk(sa0[12], sa0[13]); a.w = cvtpk(sa0[14], sa0[15]); pf[1] = __builtin_bit_cast(bf16x8, a);
;           a.x = cvtpk(sa1[0], sa1[1]); a.y = cvtpk(sa1[2], sa1[3]); a.z = cvtpk(sa1[4], sa1[5]); a.w = cvtpk(sa1[6], sa1[7]); pf[2] = __builtin_bit_cast(bf16x8, a);
;           a.x = cvtpk(sa1[8], sa1[9]); a.y = cvtpk(sa1[10], sa1[11]); a.z = cvtpk(sa1[12], sa1[13]); a.w = cvtpk(sa1[14], sa1[15]); pf[3] = __builtin_bit_cast(bf16x8, a); }
;         __builtin_amdgcn_sched_barrier(0);
;         A_VLOAD(vfb, 1);
;         __builtin_amdgcn_sched_barrier(0);
;         A_VMMA(vfa, 0);
;         A_VLOAD(vfa, 2);
;         __builtin_amdgcn_sched_barrier(0);
;         A_VMMA(vfb, 1);
;         A_VLOAD(vfb, 3);
;         __builtin_amdgcn_sched_barrier(0);
;         A_VMMA(vfa, 2);
;         __builtin_amdgcn_sched_barrier(0);
;         A_VMMA(vfb, 3);
;     ...
;         __builtin_amdgcn_sched_barrier(0); A_BAR(); A_QKBLK();
;     ...
;         if (more) {
;             if (clsn == 1) A_NEAR(sa0, sa1, t + 1);
;             float mx_; A_ROWMAX(sa0, sa1, mx_);
;             if (__any(mx_ > 8.0f)) { const float dl = fmaxf(mx_, 0.f); const float f_ = __builtin_amdgcn_exp2f(-dl); lrun *= f_;
; #pragma unroll
;                 for (int r = 0; r < 16; ++r) { sa0[r] -= dl; sa1[r] -= dl; negc[r] -= dl; }
; #pragma unroll
;                 for (int d = 0; d < 4; ++d)
; #pragma unroll
;                     for (int r = 0; r < 16; ++r) o[d][r] *= f_; }
;         }
;         bcur = bnext; bnext = bnext + ABUF; if (bnext == 3 * ABUF) bnext = 0;
	v_mfma_f32_32x32x16_bf16 v[32:47], v[230:233], v[104:107], v[32:47]
	v_max3_f32 v243, v243, v213, v214
	v_max3_f32 v239, v239, v7, v8
	v_max3_f32 v243, v243, v215, v216
	v_max3_f32 v239, v239, v9, v10
	v_max3_f32 v243, v243, v217, v218
	v_max3_f32 v239, v239, v11, v12
	v_max3_f32 v243, v243, v219, v220
	v_max3_f32 v239, v239, v13, v14
	v_max_f32_e32 v243, v243, v221
	v_max_f32_e32 v239, v239, v15
	v_max_f32_e32 v243, v243, v239
	s_waitcnt lgkmcnt(8)
	v_mfma_f32_32x32x16_bf16 v[16:31], v[244:247], v[104:107], v[16:31]
	s_waitcnt vmcnt(0)
	v_add3_u32 v238, s38, v178, v160
	v_add3_u32 v239, s38, v180, v160
	ds_write_b128 v238, v[156:159]
	ds_write_b128 v238, v[152:155] offset:9216
	s_waitcnt lgkmcnt(8)
	v_mfma_f32_32x32x16_bf16 v[64:79], v[248:251], v[108:111], v[64:79]
	ds_write_b128 v239, v[148:151] offset:18432
	ds_write_b128 v239, v[144:147] offset:30720
	v_mov_b32_e32 v239, v243
	s_min_i32 s0, s31, 0xf80
	v_add_u32_e32 v238, s0, v181
	v_min_i32_e32 v238, 0x100f, v238
	s_waitcnt lgkmcnt(8)
	v_mfma_f32_32x32x16_bf16 v[48:63], v[184:187], v[108:111], v[48:63]
	v_permlane32_swap_b32_e32 v243, v239
	v_mad_i64_i32 v[192:193], s[0:1], v238, s51, v[162:163]
	global_load_dwordx4 v[156:159], v[192:193], off offset:1024
	global_load_dwordx4 v[152:155], v[192:193], off offset:1152
	s_waitcnt lgkmcnt(6)
	v_mfma_f32_32x32x16_bf16 v[32:47], v[188:191], v[108:111], v[32:47]
	global_load_dwordx4 v[148:151], v[192:193], off offset:2048
	global_load_dwordx4 v[144:147], v[192:193], off offset:2176
	v_max_f32_e32 v243, v243, v239
	s_waitcnt lgkmcnt(4)
	v_mfma_f32_32x32x16_bf16 v[16:31], v[222:225], v[108:111], v[16:31]
	s_mov_b32 s39, s30
	s_mov_b32 s26, s29
	s_mov_b32 s29, s38
	s_add_i32 s0, s38, 0xa800
	s_cmp_lg_u32 s0, 0x1f800
	s_cselect_b32 s38, s0, 0
	s_mov_b32 s35, s31
	v_cmp_lt_f32_e32 vcc, s10, v243
	s_cbranch_vccz .Latt1_o_noresc
	s_nop 11
	v_max_f32_e32 v243, 0, v243
	v_exp_f32_e64 v192, -v243
	v_sub_f32_e32 v80, v80, v243
	v_sub_f32_e32 v81, v81, v243
	v_sub_f32_e32 v82, v82, v243
	v_sub_f32_e32 v83, v83, v243
	v_sub_f32_e32 v84, v84, v243
	v_sub_f32_e32 v85, v85, v243
	v_sub_f32_e32 v86, v86, v243
	v_sub_f32_e32 v87, v87, v243
	v_sub_f32_e32 v88, v88, v243
	v_sub_f32_e32 v89, v89, v243
	v_sub_f32_e32 v90, v90, v243
	v_sub_f32_e32 v91, v91, v243
	v_sub_f32_e32 v92, v92, v243
	v_sub_f32_e32 v93, v93, v243
	v_sub_f32_e32 v94, v94, v243
	v_sub_f32_e32 v95, v95, v243
	v_sub_f32_e32 v206, v206, v243
	v_sub_f32_e32 v207, v207, v243
	v_sub_f32_e32 v208, v208, v243
	v_sub_f32_e32 v209, v209, v243
	v_sub_f32_e32 v210, v210, v243
	v_sub_f32_e32 v211, v211, v243
	v_sub_f32_e32 v212, v212, v243
	v_sub_f32_e32 v213, v213, v243
	v_sub_f32_e32 v214, v214, v243
	v_sub_f32_e32 v215, v215, v243
	v_sub_f32_e32 v216, v216, v243
	v_sub_f32_e32 v217, v217, v243
	v_sub_f32_e32 v218, v218, v243
	v_sub_f32_e32 v219, v219, v243
	v_sub_f32_e32 v220, v220, v243
	v_sub_f32_e32 v221, v221, v243
	v_sub_f32_e32 v0, v0, v243
	v_sub_f32_e32 v1, v1, v243
	v_sub_f32_e32 v2, v2, v243
	v_sub_f32_e32 v3, v3, v243
	v_sub_f32_e32 v4, v4, v243
	v_sub_f32_e32 v5, v5, v243
	v_sub_f32_e32 v6, v6, v243
	v_sub_f32_e32 v7, v7, v243
	v_sub_f32_e32 v8, v8, v243
	v_sub_f32_e32 v9, v9, v243
	v_sub_f32_e32 v10, v10, v243
	v_sub_f32_e32 v11, v11, v243
	v_sub_f32_e32 v12, v12, v243
	v_sub_f32_e32 v13, v13, v243
	v_sub_f32_e32 v14, v14, v243
	v_sub_f32_e32 v15, v15, v243
	v_pk_mul_f32 v[64:65], v[64:65], v[192:193] op_sel_hi:[1,0]
	v_pk_mul_f32 v[66:67], v[66:67], v[192:193] op_sel_hi:[1,0]
	v_pk_mul_f32 v[68:69], v[68:69], v[192:193] op_sel_hi:[1,0]
	v_pk_mul_f32 v[70:71], v[70:71], v[192:193] op_sel_hi:[1,0]
	v_pk_mul_f32 v[72:73], v[72:73], v[192:193] op_sel_hi:[1,0]
	v_pk_mul_f32 v[74:75], v[74:75], v[192:193] op_sel_hi:[1,0]
	v_pk_mul_f32 v[76:77], v[76:77], v[192:193] op_sel_hi:[1,0]
	v_pk_mul_f32 v[78:79], v[78:79], v[192:193] op_sel_hi:[1,0]
	v_pk_mul_f32 v[48:49], v[48:49], v[192:193] op_sel_hi:[1,0]
	v_pk_mul_f32 v[50:51], v[50:51], v[192:193] op_sel_hi:[1,0]
	v_pk_mul_f32 v[52:53], v[52:53], v[192:193] op_sel_hi:[1,0]
	v_pk_mul_f32 v[54:55], v[54:55], v[192:193] op_sel_hi:[1,0]
	v_pk_mul_f32 v[56:57], v[56:57], v[192:193] op_sel_hi:[1,0]
	v_pk_mul_f32 v[58:59], v[58:59], v[192:193] op_sel_hi:[1,0]
	v_pk_mul_f32 v[60:61], v[60:61], v[192:193] op_sel_hi:[1,0]
	v_pk_mul_f32 v[62:63], v[62:63], v[192:193] op_sel_hi:[1,0]
	v_pk_mul_f32 v[32:33], v[32:33], v[192:193] op_sel_hi:[1,0]
	v_pk_mul_f32 v[34:35], v[34:35], v[192:193] op_sel_hi:[1,0]
	v_pk_mul_f32 v[36:37], v[36:37], v[192:193] op_sel_hi:[1,0]
	v_pk_mul_f32 v[38:39], v[38:39], v[192:193] op_sel_hi:[1,0]
	v_pk_mul_f32 v[40:41], v[40:41], v[192:193] op_sel_hi:[1,0]
	v_pk_mul_f32 v[42:43], v[42:43], v[192:193] op_sel_hi:[1,0]
	v_pk_mul_f32 v[44:45], v[44:45], v[192:193] op_sel_hi:[1,0]
	v_pk_mul_f32 v[46:47], v[46:47], v[192:193] op_sel_hi:[1,0]
	v_pk_mul_f32 v[16:17], v[16:17], v[192:193] op_sel_hi:[1,0]
	v_pk_mul_f32 v[18:19], v[18:19], v[192:193] op_sel_hi:[1,0]
	v_pk_mul_f32 v[20:21], v[20:21], v[192:193] op_sel_hi:[1,0]
	v_pk_mul_f32 v[22:23], v[22:23], v[192:193] op_sel_hi:[1,0]
	v_pk_mul_f32 v[24:25], v[24:25], v[192:193] op_sel_hi:[1,0]
	v_pk_mul_f32 v[26:27], v[26:27], v[192:193] op_sel_hi:[1,0]
	v_pk_mul_f32 v[28:29], v[28:29], v[192:193] op_sel_hi:[1,0]
	v_pk_mul_f32 v[30:31], v[30:31], v[192:193] op_sel_hi:[1,0]
	v_mul_f32_e32 v179, v179, v192
	v_mul_f32_e32 v202, v202, v192
	s_nop 1

; __device__ __forceinline__ unsigned cvtpk(float lo, float hi) { f32x2_t v = {lo, hi}; bf16x2_t b = __builtin_convertvector(v, bf16x2_t); return __builtin_bit_cast(unsigned, b); }
; #define A_BAR() asm volatile("s_waitcnt lgkmcnt(0)\n\ts_barrier" ::: "memory")
; __device__ __forceinline__ void attn_unit_A(const AttnP& P, int u, LAS char* lds) {
;     ...
;         float sacc = 0.f;
; #pragma unroll
;         for (int r = 0; r < 16; ++r) { sa0[r] = __builtin_amdgcn_exp2f(sa0[r]); sa1[r] = __builtin_amdgcn_exp2f(sa1[r]); sacc += sa0[r] + sa1[r]; }
;         lrun += sacc;
;         bf16x8 pf[4];
;         { u32x4 a;
;           a.x = cvtpk(sa0[0], sa0[1]); a.y = cvtpk(sa0[2], sa0[3]); a.z = cvtpk(sa0[4], sa0[5]); a.w = cvtpk(sa0[6], sa0[7]); pf[0] = __builtin_bit_cast(bf16x8, a);
;           a.x = cvtpk(sa0[8], sa0[9]); a.y = cvtpk(sa0[10], sa0[11]); a.z = cvtpk(sa0[12], sa0[13]); a.w = cvtpk(sa0[14], sa0[15]); pf[1] = __builtin_bit_cast(bf16x8, a);
;           a.x = cvtpk(sa1[0], sa1[1]); a.y = cvtpk(sa1[2], sa1[3]); a.z = cvtpk(sa1[4], sa1[5]); a.w = cvtpk(sa1[6], sa1[7]); pf[2] = __builtin_bit_cast(bf16x8, a);
;           a.x = cvtpk(sa1[8], sa1[9]); a.y = cvtpk(sa1[10], sa1[11]); a.z = cvtpk(sa1[12], sa1[13]); a.w = cvtpk(sa1[14], sa1[15]); pf[3] = __builtin_bit_cast(bf16x8, a); }
;         __builtin_amdgcn_sched_barrier(0);
;         A_VLOAD(vfb, 1);
;         __builtin_amdgcn_sched_barrier(0);
;         A_VMMA(vfa, 0);
;         A_VLOAD(vfa, 2);
;         __builtin_amdgcn_sched_barrier(0);
;         A_VMMA(vfb, 1);
;         A_VLOAD(vfb, 3);
;         __builtin_amdgcn_sched_barrier(0);
;         A_VMMA(vfa, 2);
;         __builtin_amdgcn_sched_barrier(0);
;         A_VMMA(vfb, 3);
;     ...
;         __builtin_amdgcn_sched_barrier(0); A_BAR(); A_QKBLK();
;     ...
;         if (more) {
;             if (clsn == 1) A_NEAR(sa0, sa1, t + 1);
;             float mx_; A_ROWMAX(sa0, sa1, mx_);
;             if (__any(mx_ > 8.0f)) { const float dl = fmaxf(mx_, 0.f); const float f_ = __builtin_amdgcn_exp2f(-dl); lrun *= f_;
; #pragma unroll
;                 for (int r = 0; r < 16; ++r) { sa0[r] -= dl; sa1[r] -= dl; negc[r] -= dl; }
; #pragma unroll
;                 for (int d = 0; d < 4; ++d)
; #pragma unroll
;                     for (int r = 0; r < 16; ++r) o[d][r] *= f_; }
;         }
;         bcur = bnext; bnext = bnext + ABUF; if (bnext == 3 * ABUF) bnext = 0;
.Latt2_e_join:
	s_waitcnt lgkmcnt(7)
	v_mfma_f32_32x32x16_bf16 v[96:111], v[186:189], v[136:139], v[96:111]
	ds_read_b64_tr_b16 v[186:187], v235 offset:18496
	ds_read_b64_tr_b16 v[188:189], v235 offset:20032
	v_add_f32_e32 v173, v173, v210
	v_add_f32_e32 v202, v202, v211
	v_add_f32_e32 v173, v173, v212
	v_add_f32_e32 v202, v202, v213
	v_exp_f32_e32 v214, v214
	s_waitcnt lgkmcnt(8)
	v_mfma_f32_32x32x16_bf16 v[112:127], v[190:193], v[136:139], v[112:127]
	ds_read_b64_tr_b16 v[190:191], v235 offset:30720
	ds_read_b64_tr_b16 v[192:193], v235 offset:32256
	v_cvt_pk_bf16_f32 v206, v206, v207
	v_cvt_pk_bf16_f32 v207, v208, v209
	v_cvt_pk_bf16_f32 v208, v210, v211
	v_cvt_pk_bf16_f32 v209, v212, v213
	v_exp_f32_e32 v215, v215
	s_waitcnt lgkmcnt(9)
	v_mfma_f32_32x32x16_bf16 v[96:111], v[222:225], v[132:135], v[96:111]
	ds_read_b64_tr_b16 v[222:223], v235 offset:30784
	ds_read_b64_tr_b16 v[224:225], v235 offset:32320
	v_exp_f32_e32 v216, v216
	v_exp_f32_e32 v217, v217
	v_exp_f32_e32 v218, v218
	s_waitcnt lgkmcnt(10)
	v_mfma_f32_32x32x16_bf16 v[112:127], v[226:229], v[132:135], v[112:127]
	ds_read_b64_tr_b16 v[226:227], v235 offset:21504
	ds_read_b64_tr_b16 v[228:229], v235 offset:23040
	v_exp_f32_e32 v219, v219
	v_exp_f32_e32 v220, v220
	v_exp_f32_e32 v221, v221
	s_waitcnt lgkmcnt(11)
	v_mfma_f32_32x32x16_bf16 v[96:111], v[230:233], v[128:131], v[96:111]
	ds_read_b64_tr_b16 v[230:231], v235 offset:21568
	ds_read_b64_tr_b16 v[232:233], v235 offset:23104
	v_add_f32_e32 v173, v173, v214
	v_add_f32_e32 v202, v202, v215
	v_add_f32_e32 v173, v173, v216
	v_add_f32_e32 v202, v202, v217
	v_add_f32_e32 v173, v173, v218
	v_add_f32_e32 v202, v202, v219
	s_waitcnt lgkmcnt(12)
	v_mfma_f32_32x32x16_bf16 v[112:127], v[178:181], v[128:131], v[112:127]
	ds_read_b64_tr_b16 v[178:179], v235 offset:33792
	ds_read_b64_tr_b16 v[180:181], v235 offset:35328
	v_add_f32_e32 v173, v173, v220
	v_add_f32_e32 v202, v202, v221
	v_cvt_pk_bf16_f32 v210, v214, v215
	v_cvt_pk_bf16_f32 v211, v216, v217
	v_cvt_pk_bf16_f32 v212, v218, v219
	v_cvt_pk_bf16_f32 v213, v220, v221
	s_waitcnt lgkmcnt(12)
	v_mfma_f32_32x32x16_bf16 v[64:79], v[182:185], v[206:209], v[64:79]
	ds_read_b64_tr_b16 v[182:183], v235 offset:33856
	ds_read_b64_tr_b16 v[184:185], v235 offset:35392
	v_exp_f32_e32 v0, v0
	v_exp_f32_e32 v1, v1
	v_exp_f32_e32 v2, v2
	s_waitcnt lgkmcnt(12)
	v_mfma_f32_32x32x16_bf16 v[48:63], v[186:189], v[206:209], v[48:63]
	ds_read_b64_tr_b16 v[186:187], v235 offset:24576
	ds_read_b64_tr_b16 v[188:189], v235 offset:26112
	v_exp_f32_e32 v3, v3
	v_exp_f32_e32 v4, v4
	v_exp_f32_e32 v5, v5
	s_waitcnt lgkmcnt(12)
	v_mfma_f32_32x32x16_bf16 v[32:47], v[190:193], v[206:209], v[32:47]
	ds_read_b64_tr_b16 v[190:191], v235 offset:24640
	ds_read_b64_tr_b16 v[192:193], v235 offset:26176
	v_exp_f32_e32 v6, v6
	v_exp_f32_e32 v7, v7
	v_add_f32_e32 v173, v173, v0
	v_add_f32_e32 v202, v202, v1
	s_waitcnt lgkmcnt(12)
	v_mfma_f32_32x32x16_bf16 v[16:31], v[222:225], v[206:209], v[16:31]
	ds_read_b64_tr_b16 v[222:223], v235 offset:36864
	ds_read_b64_tr_b16 v[224:225], v235 offset:38400
	v_add_f32_e32 v173, v173, v2
	v_add_f32_e32 v202, v202, v3
	v_add_f32_e32 v173, v173, v4
	v_add_f32_e32 v202, v202, v5
	v_add_f32_e32 v173, v173, v6
	v_add_f32_e32 v202, v202, v7
	s_waitcnt lgkmcnt(12)
	v_mfma_f32_32x32x16_bf16 v[64:79], v[226:229], v[210:213], v[64:79]
	ds_read_b64_tr_b16 v[226:227], v235 offset:36928
	ds_read_b64_tr_b16 v[228:229], v235 offset:38464
	v_cvt_pk_bf16_f32 v214, v0, v1
	v_cvt_pk_bf16_f32 v215, v2, v3
	v_cvt_pk_bf16_f32 v216, v4, v5
	v_cvt_pk_bf16_f32 v217, v6, v7
	v_exp_f32_e32 v8, v8
	s_waitcnt lgkmcnt(12)
	v_mfma_f32_32x32x16_bf16 v[48:63], v[230:233], v[210:213], v[48:63]
	ds_read_b64_tr_b16 v[230:231], v235 offset:27648
	ds_read_b64_tr_b16 v[232:233], v235 offset:29184
	v_exp_f32_e32 v9, v9
	v_exp_f32_e32 v10, v10
	v_exp_f32_e32 v11, v11
	s_waitcnt lgkmcnt(12)
	v_mfma_f32_32x32x16_bf16 v[32:47], v[178:181], v[210:213], v[32:47]
	ds_read_b64_tr_b16 v[178:179], v235 offset:27712
	ds_read_b64_tr_b16 v[180:181], v235 offset:29248
	v_exp_f32_e32 v12, v12
	v_exp_f32_e32 v13, v13
	v_exp_f32_e32 v14, v14
	s_waitcnt lgkmcnt(12)
	v_mfma_f32_32x32x16_bf16 v[16:31], v[182:185], v[210:213], v[16:31]
	ds_read_b64_tr_b16 v[182:183], v235 offset:39936
	ds_read_b64_tr_b16 v[184:185], v235 offset:41472
	v_exp_f32_e32 v15, v15
	v_add_f32_e32 v173, v173, v8
	v_add_f32_e32 v202, v202, v9
	v_add_f32_e32 v173, v173, v10
	v_add_f32_e32 v202, v202, v11
	s_waitcnt lgkmcnt(12)
	v_mfma_f32_32x32x16_bf16 v[64:79], v[186:189], v[214:217], v[64:79]
	ds_read_b64_tr_b16 v[186:187], v235 offset:40000
	ds_read_b64_tr_b16 v[188:189], v235 offset:41536
	v_add_f32_e32 v173, v173, v12
	v_add_f32_e32 v202, v202, v13
	v_add_f32_e32 v173, v173, v14
	v_add_f32_e32 v202, v202, v15
	v_max3_f32 v243, v96, v97, v98
	v_max3_f32 v239, v112, v113, v114
	s_waitcnt lgkmcnt(12)
	v_mfma_f32_32x32x16_bf16 v[48:63], v[190:193], v[214:217], v[48:63]
	v_cvt_pk_bf16_f32 v218, v8, v9
	v_cvt_pk_bf16_f32 v219, v10, v11
	v_cvt_pk_bf16_f32 v220, v12, v13
	v_cvt_pk_bf16_f32 v221, v14, v15
	v_max3_f32 v243, v243, v99, v100
	v_max3_f32 v239, v239, v115, v116
	v_max3_f32 v243, v243, v101, v102
	v_max3_f32 v239, v239, v117, v118
	s_waitcnt lgkmcnt(10)
; __device__ __forceinline__ unsigned cvtpk(float lo, float hi) { f32x2_t v = {lo, hi}; bf16x2_t b = __builtin_convertvector(v, bf16x2_t); return __builtin_bit_cast(unsigned, b); }
; #define A_BAR() asm volatile("s_waitcnt lgkmcnt(0)\n\ts_barrier" ::: "memory")
; __device__ __forceinline__ void attn_unit_A(const AttnP& P, int u, LAS char* lds) {
;     ...
;         float sacc = 0.f;
; #pragma unroll
;         for (int r = 0; r < 16; ++r) { sa0[r] = __builtin_amdgcn_exp2f(sa0[r]); sa1[r] = __builtin_amdgcn_exp2f(sa1[r]); sacc += sa0[r] + sa1[r]; }
;         lrun += sacc;
;         bf16x8 pf[4];
;         { u32x4 a;
;           a.x = cvtpk(sa0[0], sa0[1]); a.y = cvtpk(sa0[2], sa0[3]); a.z = cvtpk(sa0[4], sa0[5]); a.w = cvtpk(sa0[6], sa0[7]); pf[0] = __builtin_bit_cast(bf16x8, a);
;           a.x = cvtpk(sa0[8], sa0[9]); a.y = cvtpk(sa0[10], sa0[11]); a.z = cvtpk(sa0[12], sa0[13]); a.w = cvtpk(sa0[14], sa0[15]); pf[1] = __builtin_bit_cast(bf16x8, a);
;           a.x = cvtpk(sa1[0], sa1[1]); a.y = cvtpk(sa1[2], sa1[3]); a.z = cvtpk(sa1[4], sa1[5]); a.w = cvtpk(sa1[6], sa1[7]); pf[2] = __builtin_bit_cast(bf16x8, a);
;           a.x = cvtpk(sa1[8], sa1[9]); a.y = cvtpk(sa1[10], sa1[11]); a.z = cvtpk(sa1[12], sa1[13]); a.w = cvtpk(sa1[14], sa1[15]); pf[3] = __builtin_bit_cast(bf16x8, a); }
;         __builtin_amdgcn_sched_barrier(0);
;         A_VLOAD(vfb, 1);
;         __builtin_amdgcn_sched_barrier(0);
;         A_VMMA(vfa, 0);
;         A_VLOAD(vfa, 2);
;         __builtin_amdgcn_sched_barrier(0);
;         A_VMMA(vfb, 1);
;         A_VLOAD(vfb, 3);
;         __builtin_amdgcn_sched_barrier(0);
;         A_VMMA(vfa, 2);
;         __builtin_amdgcn_sched_barrier(0);
;         A_VMMA(vfb, 3);
;     ...
;         __builtin_amdgcn_sched_barrier(0); A_BAR(); A_QKBLK();
;     ...
;         if (more) {
;             if (clsn == 1) A_NEAR(sa0, sa1, t + 1);
;             float mx_; A_ROWMAX(sa0, sa1, mx_);
;             if (__any(mx_ > 8.0f)) { const float dl = fmaxf(mx_, 0.f); const float f_ = __builtin_amdgcn_exp2f(-dl); lrun *= f_;
; #pragma unroll
;                 for (int r = 0; r < 16; ++r) { sa0[r] -= dl; sa1[r] -= dl; negc[r] -= dl; }
; #pragma unroll
;                 for (int d = 0; d < 4; ++d)
; #pragma unroll
;                     for (int r = 0; r < 16; ++r) o[d][r] *= f_; }
;         }
;         bcur = bnext; bnext = bnext + ABUF; if (bnext == 3 * ABUF) bnext = 0;
	v_mfma_f32_32x32x16_bf16 v[32:47], v[222:225], v[214:217], v[32:47]
	v_max3_f32 v243, v243, v103, v104
	v_max3_f32 v239, v239, v119, v120
	v_max3_f32 v243, v243, v105, v106
	v_max3_f32 v239, v239, v121, v122
	v_max3_f32 v243, v243, v107, v108
	v_max3_f32 v239, v239, v123, v124
	v_max3_f32 v243, v243, v109, v110
	v_max3_f32 v239, v239, v125, v126
	v_max_f32_e32 v243, v243, v111
	v_max_f32_e32 v239, v239, v127
	v_max_f32_e32 v243, v243, v239
	s_waitcnt lgkmcnt(8)
	v_mfma_f32_32x32x16_bf16 v[16:31], v[226:229], v[214:217], v[16:31]
	s_waitcnt vmcnt(0)
	v_add3_u32 v238, s35, v172, v160
	v_add3_u32 v239, s35, v174, v160
	ds_write_b128 v238, v[156:159]
	ds_write_b128 v238, v[152:155] offset:9216
	s_waitcnt lgkmcnt(8)
	v_mfma_f32_32x32x16_bf16 v[64:79], v[230:233], v[218:221], v[64:79]
	ds_write_b128 v239, v[148:151] offset:18432
	ds_write_b128 v239, v[144:147] offset:30720
	v_mov_b32_e32 v239, v243
	s_min_i32 s0, s30, 0xf80
	v_add_u32_e32 v238, s0, v175
	v_min_i32_e32 v238, 0x100f, v238
	s_waitcnt lgkmcnt(8)
	v_mfma_f32_32x32x16_bf16 v[48:63], v[178:181], v[218:221], v[48:63]
	v_permlane32_swap_b32_e32 v243, v239
	v_mad_i64_i32 v[244:245], s[0:1], v238, s51, v[162:163]
	global_load_dwordx4 v[156:159], v[244:245], off offset:1024
	global_load_dwordx4 v[152:155], v[244:245], off offset:1152
	s_waitcnt lgkmcnt(6)
	v_mfma_f32_32x32x16_bf16 v[32:47], v[182:185], v[218:221], v[32:47]
	global_load_dwordx4 v[148:151], v[244:245], off offset:2048
	global_load_dwordx4 v[144:147], v[244:245], off offset:2176
	v_max_f32_e32 v243, v243, v239
	s_waitcnt lgkmcnt(4)
	v_mfma_f32_32x32x16_bf16 v[16:31], v[186:189], v[218:221], v[16:31]
	s_mov_b32 s34, s29
	s_mov_b32 s26, s28
	s_mov_b32 s28, s35
	s_add_i32 s0, s35, 0xa800
	s_cmp_lg_u32 s0, 0x1f800
	s_cselect_b32 s35, s0, 0
	s_mov_b32 s31, s30
	v_cmp_lt_f32_e32 vcc, s10, v243
	s_cbranch_vccz .Latt2_e_noresc
	s_nop 11
	v_max_f32_e32 v243, 0, v243
	v_exp_f32_e64 v244, -v243
	v_sub_f32_e32 v80, v80, v243
	v_sub_f32_e32 v81, v81, v243
	v_sub_f32_e32 v82, v82, v243
	v_sub_f32_e32 v83, v83, v243
	v_sub_f32_e32 v84, v84, v243
	v_sub_f32_e32 v85, v85, v243
	v_sub_f32_e32 v86, v86, v243
	v_sub_f32_e32 v87, v87, v243
	v_sub_f32_e32 v88, v88, v243
	v_sub_f32_e32 v89, v89, v243
	v_sub_f32_e32 v90, v90, v243
	v_sub_f32_e32 v91, v91, v243
	v_sub_f32_e32 v92, v92, v243
	v_sub_f32_e32 v93, v93, v243
	v_sub_f32_e32 v94, v94, v243
	v_sub_f32_e32 v95, v95, v243
	v_sub_f32_e32 v96, v96, v243
	v_sub_f32_e32 v97, v97, v243
	v_sub_f32_e32 v98, v98, v243
	v_sub_f32_e32 v99, v99, v243
	v_sub_f32_e32 v100, v100, v243
	v_sub_f32_e32 v101, v101, v243
	v_sub_f32_e32 v102, v102, v243
	v_sub_f32_e32 v103, v103, v243
	v_sub_f32_e32 v104, v104, v243
	v_sub_f32_e32 v105, v105, v243
	v_sub_f32_e32 v106, v106, v243
	v_sub_f32_e32 v107, v107, v243
	v_sub_f32_e32 v108, v108, v243
	v_sub_f32_e32 v109, v109, v243
	v_sub_f32_e32 v110, v110, v243
	v_sub_f32_e32 v111, v111, v243
	v_sub_f32_e32 v112, v112, v243
	v_sub_f32_e32 v113, v113, v243
	v_sub_f32_e32 v114, v114, v243
	v_sub_f32_e32 v115, v115, v243
	v_sub_f32_e32 v116, v116, v243
	v_sub_f32_e32 v117, v117, v243
	v_sub_f32_e32 v118, v118, v243
	v_sub_f32_e32 v119, v119, v243
	v_sub_f32_e32 v120, v120, v243
	v_sub_f32_e32 v121, v121, v243
	v_sub_f32_e32 v122, v122, v243
	v_sub_f32_e32 v123, v123, v243
	v_sub_f32_e32 v124, v124, v243
	v_sub_f32_e32 v125, v125, v243
	v_sub_f32_e32 v126, v126, v243
	v_sub_f32_e32 v127, v127, v243
	v_pk_mul_f32 v[64:65], v[64:65], v[244:245] op_sel_hi:[1,0]
	v_pk_mul_f32 v[66:67], v[66:67], v[244:245] op_sel_hi:[1,0]
	v_pk_mul_f32 v[68:69], v[68:69], v[244:245] op_sel_hi:[1,0]
	v_pk_mul_f32 v[70:71], v[70:71], v[244:245] op_sel_hi:[1,0]
	v_pk_mul_f32 v[72:73], v[72:73], v[244:245] op_sel_hi:[1,0]
	v_pk_mul_f32 v[74:75], v[74:75], v[244:245] op_sel_hi:[1,0]
	v_pk_mul_f32 v[76:77], v[76:77], v[244:245] op_sel_hi:[1,0]
	v_pk_mul_f32 v[78:79], v[78:79], v[244:245] op_sel_hi:[1,0]
	v_pk_mul_f32 v[48:49], v[48:49], v[244:245] op_sel_hi:[1,0]
	v_pk_mul_f32 v[50:51], v[50:51], v[244:245] op_sel_hi:[1,0]
	v_pk_mul_f32 v[52:53], v[52:53], v[244:245] op_sel_hi:[1,0]
	v_pk_mul_f32 v[54:55], v[54:55], v[244:245] op_sel_hi:[1,0]
	v_pk_mul_f32 v[56:57], v[56:57], v[244:245] op_sel_hi:[1,0]
	v_pk_mul_f32 v[58:59], v[58:59], v[244:245] op_sel_hi:[1,0]
	v_pk_mul_f32 v[60:61], v[60:61], v[244:245] op_sel_hi:[1,0]
	v_pk_mul_f32 v[62:63], v[62:63], v[244:245] op_sel_hi:[1,0]
	v_pk_mul_f32 v[32:33], v[32:33], v[244:245] op_sel_hi:[1,0]
	v_pk_mul_f32 v[34:35], v[34:35], v[244:245] op_sel_hi:[1,0]
	v_pk_mul_f32 v[36:37], v[36:37], v[244:245] op_sel_hi:[1,0]
	v_pk_mul_f32 v[38:39], v[38:39], v[244:245] op_sel_hi:[1,0]
	v_pk_mul_f32 v[40:41], v[40:41], v[244:245] op_sel_hi:[1,0]
	v_pk_mul_f32 v[42:43], v[42:43], v[244:245] op_sel_hi:[1,0]
	v_pk_mul_f32 v[44:45], v[44:45], v[244:245] op_sel_hi:[1,0]
	v_pk_mul_f32 v[46:47], v[46:47], v[244:245] op_sel_hi:[1,0]
	v_pk_mul_f32 v[16:17], v[16:17], v[244:245] op_sel_hi:[1,0]
	v_pk_mul_f32 v[18:19], v[18:19], v[244:245] op_sel_hi:[1,0]
	v_pk_mul_f32 v[20:21], v[20:21], v[244:245] op_sel_hi:[1,0]
	v_pk_mul_f32 v[22:23], v[22:23], v[244:245] op_sel_hi:[1,0]
	v_pk_mul_f32 v[24:25], v[24:25], v[244:245] op_sel_hi:[1,0]
	v_pk_mul_f32 v[26:27], v[26:27], v[244:245] op_sel_hi:[1,0]
	v_pk_mul_f32 v[28:29], v[28:29], v[244:245] op_sel_hi:[1,0]
	v_pk_mul_f32 v[30:31], v[30:31], v[244:245] op_sel_hi:[1,0]
	v_mul_f32_e32 v173, v173, v244
	v_mul_f32_e32 v202, v202, v244
	s_nop 1

; __device__ __forceinline__ unsigned cvtpk(float lo, float hi) { f32x2_t v = {lo, hi}; bf16x2_t b = __builtin_convertvector(v, bf16x2_t); return __builtin_bit_cast(unsigned, b); }
; #define A_BAR() asm volatile("s_waitcnt lgkmcnt(0)\n\ts_barrier" ::: "memory")
; __device__ __forceinline__ void attn_unit_A(const AttnP& P, int u, LAS char* lds) {
;     ...
;         float sacc = 0.f;
; #pragma unroll
;         for (int r = 0; r < 16; ++r) { sa0[r] = __builtin_amdgcn_exp2f(sa0[r]); sa1[r] = __builtin_amdgcn_exp2f(sa1[r]); sacc += sa0[r] + sa1[r]; }
;         lrun += sacc;
;         bf16x8 pf[4];
;         { u32x4 a;
;           a.x = cvtpk(sa0[0], sa0[1]); a.y = cvtpk(sa0[2], sa0[3]); a.z = cvtpk(sa0[4], sa0[5]); a.w = cvtpk(sa0[6], sa0[7]); pf[0] = __builtin_bit_cast(bf16x8, a);
;           a.x = cvtpk(sa0[8], sa0[9]); a.y = cvtpk(sa0[10], sa0[11]); a.z = cvtpk(sa0[12], sa0[13]); a.w = cvtpk(sa0[14], sa0[15]); pf[1] = __builtin_bit_cast(bf16x8, a);
;           a.x = cvtpk(sa1[0], sa1[1]); a.y = cvtpk(sa1[2], sa1[3]); a.z = cvtpk(sa1[4], sa1[5]); a.w = cvtpk(sa1[6], sa1[7]); pf[2] = __builtin_bit_cast(bf16x8, a);
;           a.x = cvtpk(sa1[8], sa1[9]); a.y = cvtpk(sa1[10], sa1[11]); a.z = cvtpk(sa1[12], sa1[13]); a.w = cvtpk(sa1[14], sa1[15]); pf[3] = __builtin_bit_cast(bf16x8, a); }
;         __builtin_amdgcn_sched_barrier(0);
;         A_VLOAD(vfb, 1);
;         __builtin_amdgcn_sched_barrier(0);
;         A_VMMA(vfa, 0);
;         A_VLOAD(vfa, 2);
;         __builtin_amdgcn_sched_barrier(0);
;         A_VMMA(vfb, 1);
;         A_VLOAD(vfb, 3);
;         __builtin_amdgcn_sched_barrier(0);
;         A_VMMA(vfa, 2);
;         __builtin_amdgcn_sched_barrier(0);
;         A_VMMA(vfb, 3);
;     ...
;         __builtin_amdgcn_sched_barrier(0); A_BAR(); A_QKBLK();
;     ...
;         if (more) {
;             if (clsn == 1) A_NEAR(sa0, sa1, t + 1);
;             float mx_; A_ROWMAX(sa0, sa1, mx_);
;             if (__any(mx_ > 8.0f)) { const float dl = fmaxf(mx_, 0.f); const float f_ = __builtin_amdgcn_exp2f(-dl); lrun *= f_;
; #pragma unroll
;                 for (int r = 0; r < 16; ++r) { sa0[r] -= dl; sa1[r] -= dl; negc[r] -= dl; }
; #pragma unroll
;                 for (int d = 0; d < 4; ++d)
; #pragma unroll
;                     for (int r = 0; r < 16; ++r) o[d][r] *= f_; }
;         }
;         bcur = bnext; bnext = bnext + ABUF; if (bnext == 3 * ABUF) bnext = 0;
.Latt2_o_join:
	s_waitcnt lgkmcnt(7)
	v_mfma_f32_32x32x16_bf16 v[206:221], v[186:189], v[136:139], v[206:221]
	ds_read_b64_tr_b16 v[186:187], v235 offset:18496
	ds_read_b64_tr_b16 v[188:189], v235 offset:20032
	v_add_f32_e32 v173, v173, v100
	v_add_f32_e32 v202, v202, v101
	v_add_f32_e32 v173, v173, v102
	v_add_f32_e32 v202, v202, v103
	v_exp_f32_e32 v104, v104
	s_waitcnt lgkmcnt(8)
	v_mfma_f32_32x32x16_bf16 v[0:15], v[190:193], v[136:139], v[0:15]
	ds_read_b64_tr_b16 v[190:191], v235 offset:30720
	ds_read_b64_tr_b16 v[192:193], v235 offset:32256
	v_cvt_pk_bf16_f32 v96, v96, v97
	v_cvt_pk_bf16_f32 v97, v98, v99
	v_cvt_pk_bf16_f32 v98, v100, v101
	v_cvt_pk_bf16_f32 v99, v102, v103
	v_exp_f32_e32 v105, v105
	s_waitcnt lgkmcnt(9)
	v_mfma_f32_32x32x16_bf16 v[206:221], v[222:225], v[132:135], v[206:221]
	ds_read_b64_tr_b16 v[222:223], v235 offset:30784
	ds_read_b64_tr_b16 v[224:225], v235 offset:32320
	v_exp_f32_e32 v106, v106
	v_exp_f32_e32 v107, v107
	v_exp_f32_e32 v108, v108
	s_waitcnt lgkmcnt(10)
	v_mfma_f32_32x32x16_bf16 v[0:15], v[226:229], v[132:135], v[0:15]
	ds_read_b64_tr_b16 v[226:227], v235 offset:21504
	ds_read_b64_tr_b16 v[228:229], v235 offset:23040
	v_exp_f32_e32 v109, v109
	v_exp_f32_e32 v110, v110
	v_exp_f32_e32 v111, v111
	s_waitcnt lgkmcnt(11)
	v_mfma_f32_32x32x16_bf16 v[206:221], v[230:233], v[128:131], v[206:221]
	ds_read_b64_tr_b16 v[230:231], v235 offset:21568
	ds_read_b64_tr_b16 v[232:233], v235 offset:23104
	v_add_f32_e32 v173, v173, v104
	v_add_f32_e32 v202, v202, v105
	v_add_f32_e32 v173, v173, v106
	v_add_f32_e32 v202, v202, v107
	v_add_f32_e32 v173, v173, v108
	v_add_f32_e32 v202, v202, v109
	s_waitcnt lgkmcnt(12)
	v_mfma_f32_32x32x16_bf16 v[0:15], v[178:181], v[128:131], v[0:15]
	ds_read_b64_tr_b16 v[178:179], v235 offset:33792
	ds_read_b64_tr_b16 v[180:181], v235 offset:35328
	v_add_f32_e32 v173, v173, v110
	v_add_f32_e32 v202, v202, v111
	v_cvt_pk_bf16_f32 v100, v104, v105
	v_cvt_pk_bf16_f32 v101, v106, v107
	v_cvt_pk_bf16_f32 v102, v108, v109
	v_cvt_pk_bf16_f32 v103, v110, v111
	s_waitcnt lgkmcnt(12)
	v_mfma_f32_32x32x16_bf16 v[64:79], v[182:185], v[96:99], v[64:79]
	ds_read_b64_tr_b16 v[182:183], v235 offset:33856
	ds_read_b64_tr_b16 v[184:185], v235 offset:35392
	v_exp_f32_e32 v112, v112
	v_exp_f32_e32 v113, v113
	v_exp_f32_e32 v114, v114
	s_waitcnt lgkmcnt(12)
	v_mfma_f32_32x32x16_bf16 v[48:63], v[186:189], v[96:99], v[48:63]
	ds_read_b64_tr_b16 v[186:187], v235 offset:24576
	ds_read_b64_tr_b16 v[188:189], v235 offset:26112
	v_exp_f32_e32 v115, v115
	v_exp_f32_e32 v116, v116
	v_exp_f32_e32 v117, v117
	s_waitcnt lgkmcnt(12)
	v_mfma_f32_32x32x16_bf16 v[32:47], v[190:193], v[96:99], v[32:47]
	ds_read_b64_tr_b16 v[190:191], v235 offset:24640
	ds_read_b64_tr_b16 v[192:193], v235 offset:26176
	v_exp_f32_e32 v118, v118
	v_exp_f32_e32 v119, v119
	v_add_f32_e32 v173, v173, v112
	v_add_f32_e32 v202, v202, v113
	s_waitcnt lgkmcnt(12)
	v_mfma_f32_32x32x16_bf16 v[16:31], v[222:225], v[96:99], v[16:31]
	ds_read_b64_tr_b16 v[222:223], v235 offset:36864
	ds_read_b64_tr_b16 v[224:225], v235 offset:38400
	v_add_f32_e32 v173, v173, v114
	v_add_f32_e32 v202, v202, v115
	v_add_f32_e32 v173, v173, v116
	v_add_f32_e32 v202, v202, v117
	v_add_f32_e32 v173, v173, v118
	v_add_f32_e32 v202, v202, v119
	s_waitcnt lgkmcnt(12)
	v_mfma_f32_32x32x16_bf16 v[64:79], v[226:229], v[100:103], v[64:79]
	ds_read_b64_tr_b16 v[226:227], v235 offset:36928
	ds_read_b64_tr_b16 v[228:229], v235 offset:38464
	v_cvt_pk_bf16_f32 v104, v112, v113
	v_cvt_pk_bf16_f32 v105, v114, v115
	v_cvt_pk_bf16_f32 v106, v116, v117
	v_cvt_pk_bf16_f32 v107, v118, v119
	v_exp_f32_e32 v120, v120
	s_waitcnt lgkmcnt(12)
	v_mfma_f32_32x32x16_bf16 v[48:63], v[230:233], v[100:103], v[48:63]
	ds_read_b64_tr_b16 v[230:231], v235 offset:27648
	ds_read_b64_tr_b16 v[232:233], v235 offset:29184
	v_exp_f32_e32 v121, v121
	v_exp_f32_e32 v122, v122
	v_exp_f32_e32 v123, v123
	s_waitcnt lgkmcnt(12)
	v_mfma_f32_32x32x16_bf16 v[32:47], v[178:181], v[100:103], v[32:47]
	ds_read_b64_tr_b16 v[178:179], v235 offset:27712
	ds_read_b64_tr_b16 v[180:181], v235 offset:29248
	v_exp_f32_e32 v124, v124
	v_exp_f32_e32 v125, v125
	v_exp_f32_e32 v126, v126
	s_waitcnt lgkmcnt(12)
	v_mfma_f32_32x32x16_bf16 v[16:31], v[182:185], v[100:103], v[16:31]
	ds_read_b64_tr_b16 v[182:183], v235 offset:39936
	ds_read_b64_tr_b16 v[184:185], v235 offset:41472
	v_exp_f32_e32 v127, v127
	v_add_f32_e32 v173, v173, v120
	v_add_f32_e32 v202, v202, v121
	v_add_f32_e32 v173, v173, v122
	v_add_f32_e32 v202, v202, v123
	s_waitcnt lgkmcnt(12)
	v_mfma_f32_32x32x16_bf16 v[64:79], v[186:189], v[104:107], v[64:79]
	ds_read_b64_tr_b16 v[186:187], v235 offset:40000
	ds_read_b64_tr_b16 v[188:189], v235 offset:41536
	v_add_f32_e32 v173, v173, v124
	v_add_f32_e32 v202, v202, v125
	v_add_f32_e32 v173, v173, v126
	v_add_f32_e32 v202, v202, v127
	v_max3_f32 v243, v206, v207, v208
	v_max3_f32 v239, v0, v1, v2
	s_waitcnt lgkmcnt(12)
	v_mfma_f32_32x32x16_bf16 v[48:63], v[190:193], v[104:107], v[48:63]
	v_cvt_pk_bf16_f32 v108, v120, v121
	v_cvt_pk_bf16_f32 v109, v122, v123
	v_cvt_pk_bf16_f32 v110, v124, v125
	v_cvt_pk_bf16_f32 v111, v126, v127
	v_max3_f32 v243, v243, v209, v210
	v_max3_f32 v239, v239, v3, v4
	v_max3_f32 v243, v243, v211, v212
	v_max3_f32 v239, v239, v5, v6
	s_waitcnt lgkmcnt(10)
; __device__ __forceinline__ unsigned cvtpk(float lo, float hi) { f32x2_t v = {lo, hi}; bf16x2_t b = __builtin_convertvector(v, bf16x2_t); return __builtin_bit_cast(unsigned, b); }
; #define A_BAR() asm volatile("s_waitcnt lgkmcnt(0)\n\ts_barrier" ::: "memory")
; __device__ __forceinline__ void attn_unit_A(const AttnP& P, int u, LAS char* lds) {
;     ...
;         float sacc = 0.f;
; #pragma unroll
;         for (int r = 0; r < 16; ++r) { sa0[r] = __builtin_amdgcn_exp2f(sa0[r]); sa1[r] = __builtin_amdgcn_exp2f(sa1[r]); sacc += sa0[r] + sa1[r]; }
;         lrun += sacc;
;         bf16x8 pf[4];
;         { u32x4 a;
;           a.x = cvtpk(sa0[0], sa0[1]); a.y = cvtpk(sa0[2], sa0[3]); a.z = cvtpk(sa0[4], sa0[5]); a.w = cvtpk(sa0[6], sa0[7]); pf[0] = __builtin_bit_cast(bf16x8, a);
;           a.x = cvtpk(sa0[8], sa0[9]); a.y = cvtpk(sa0[10], sa0[11]); a.z = cvtpk(sa0[12], sa0[13]); a.w = cvtpk(sa0[14], sa0[15]); pf[1] = __builtin_bit_cast(bf16x8, a);
;           a.x = cvtpk(sa1[0], sa1[1]); a.y = cvtpk(sa1[2], sa1[3]); a.z = cvtpk(sa1[4], sa1[5]); a.w = cvtpk(sa1[6], sa1[7]); pf[2] = __builtin_bit_cast(bf16x8, a);
;           a.x = cvtpk(sa1[8], sa1[9]); a.y = cvtpk(sa1[10], sa1[11]); a.z = cvtpk(sa1[12], sa1[13]); a.w = cvtpk(sa1[14], sa1[15]); pf[3] = __builtin_bit_cast(bf16x8, a); }
;         __builtin_amdgcn_sched_barrier(0);
;         A_VLOAD(vfb, 1);
;         __builtin_amdgcn_sched_barrier(0);
;         A_VMMA(vfa, 0);
;         A_VLOAD(vfa, 2);
;         __builtin_amdgcn_sched_barrier(0);
;         A_VMMA(vfb, 1);
;         A_VLOAD(vfb, 3);
;         __builtin_amdgcn_sched_barrier(0);
;         A_VMMA(vfa, 2);
;         __builtin_amdgcn_sched_barrier(0);
;         A_VMMA(vfb, 3);
;     ...
;         __builtin_amdgcn_sched_barrier(0); A_BAR(); A_QKBLK();
;     ...
;         if (more) {
;             if (clsn == 1) A_NEAR(sa0, sa1, t + 1);
;             float mx_; A_ROWMAX(sa0, sa1, mx_);
;             if (__any(mx_ > 8.0f)) { const float dl = fmaxf(mx_, 0.f); const float f_ = __builtin_amdgcn_exp2f(-dl); lrun *= f_;
; #pragma unroll
;                 for (int r = 0; r < 16; ++r) { sa0[r] -= dl; sa1[r] -= dl; negc[r] -= dl; }
; #pragma unroll
;                 for (int d = 0; d < 4; ++d)
; #pragma unroll
;                     for (int r = 0; r < 16; ++r) o[d][r] *= f_; }
;         }
;         bcur = bnext; bnext = bnext + ABUF; if (bnext == 3 * ABUF) bnext = 0;
	v_mfma_f32_32x32x16_bf16 v[32:47], v[222:225], v[104:107], v[32:47]
	v_max3_f32 v243, v243, v213, v214
	v_max3_f32 v239, v239, v7, v8
	v_max3_f32 v243, v243, v215, v216
	v_max3_f32 v239, v239, v9, v10
	v_max3_f32 v243, v243, v217, v218
	v_max3_f32 v239, v239, v11, v12
	v_max3_f32 v243, v243, v219, v220
	v_max3_f32 v239, v239, v13, v14
	v_max_f32_e32 v243, v243, v221
	v_max_f32_e32 v239, v239, v15
	v_max_f32_e32 v243, v243, v239
	s_waitcnt lgkmcnt(8)
	v_mfma_f32_32x32x16_bf16 v[16:31], v[226:229], v[104:107], v[16:31]
	s_waitcnt vmcnt(0)
	v_add3_u32 v238, s35, v172, v160
	v_add3_u32 v239, s35, v174, v160
	ds_write_b128 v238, v[156:159]
	ds_write_b128 v238, v[152:155] offset:9216
	s_waitcnt lgkmcnt(8)
	v_mfma_f32_32x32x16_bf16 v[64:79], v[230:233], v[108:111], v[64:79]
	ds_write_b128 v239, v[148:151] offset:18432
	ds_write_b128 v239, v[144:147] offset:30720
	v_mov_b32_e32 v239, v243
	s_min_i32 s0, s30, 0xf80
	v_add_u32_e32 v238, s0, v175
	v_min_i32_e32 v238, 0x100f, v238
	s_waitcnt lgkmcnt(8)
	v_mfma_f32_32x32x16_bf16 v[48:63], v[178:181], v[108:111], v[48:63]
	v_permlane32_swap_b32_e32 v243, v239
	v_mad_i64_i32 v[244:245], s[0:1], v238, s51, v[162:163]
	global_load_dwordx4 v[156:159], v[244:245], off offset:1024
	global_load_dwordx4 v[152:155], v[244:245], off offset:1152
	s_waitcnt lgkmcnt(6)
	v_mfma_f32_32x32x16_bf16 v[32:47], v[182:185], v[108:111], v[32:47]
	global_load_dwordx4 v[148:151], v[244:245], off offset:2048
	global_load_dwordx4 v[144:147], v[244:245], off offset:2176
	v_max_f32_e32 v243, v243, v239
	s_waitcnt lgkmcnt(4)
	v_mfma_f32_32x32x16_bf16 v[16:31], v[186:189], v[108:111], v[16:31]
	s_mov_b32 s34, s29
	s_mov_b32 s26, s28
	s_mov_b32 s28, s35
	s_add_i32 s0, s35, 0xa800
	s_cmp_lg_u32 s0, 0x1f800
	s_cselect_b32 s35, s0, 0
	s_mov_b32 s31, s30
	v_cmp_lt_f32_e32 vcc, s10, v243
	s_cbranch_vccz .Latt2_o_noresc
	s_nop 11
	v_max_f32_e32 v243, 0, v243
	v_exp_f32_e64 v244, -v243
	v_sub_f32_e32 v80, v80, v243
	v_sub_f32_e32 v81, v81, v243
	v_sub_f32_e32 v82, v82, v243
	v_sub_f32_e32 v83, v83, v243
	v_sub_f32_e32 v84, v84, v243
	v_sub_f32_e32 v85, v85, v243
	v_sub_f32_e32 v86, v86, v243
	v_sub_f32_e32 v87, v87, v243
	v_sub_f32_e32 v88, v88, v243
	v_sub_f32_e32 v89, v89, v243
	v_sub_f32_e32 v90, v90, v243
	v_sub_f32_e32 v91, v91, v243
	v_sub_f32_e32 v92, v92, v243
	v_sub_f32_e32 v93, v93, v243
	v_sub_f32_e32 v94, v94, v243
	v_sub_f32_e32 v95, v95, v243
	v_sub_f32_e32 v206, v206, v243
	v_sub_f32_e32 v207, v207, v243
	v_sub_f32_e32 v208, v208, v243
	v_sub_f32_e32 v209, v209, v243
	v_sub_f32_e32 v210, v210, v243
	v_sub_f32_e32 v211, v211, v243
	v_sub_f32_e32 v212, v212, v243
	v_sub_f32_e32 v213, v213, v243
	v_sub_f32_e32 v214, v214, v243
	v_sub_f32_e32 v215, v215, v243
	v_sub_f32_e32 v216, v216, v243
	v_sub_f32_e32 v217, v217, v243
	v_sub_f32_e32 v218, v218, v243
	v_sub_f32_e32 v219, v219, v243
	v_sub_f32_e32 v220, v220, v243
	v_sub_f32_e32 v221, v221, v243
	v_sub_f32_e32 v0, v0, v243
	v_sub_f32_e32 v1, v1, v243
	v_sub_f32_e32 v2, v2, v243
	v_sub_f32_e32 v3, v3, v243
	v_sub_f32_e32 v4, v4, v243
	v_sub_f32_e32 v5, v5, v243
	v_sub_f32_e32 v6, v6, v243
	v_sub_f32_e32 v7, v7, v243
	v_sub_f32_e32 v8, v8, v243
	v_sub_f32_e32 v9, v9, v243
	v_sub_f32_e32 v10, v10, v243
	v_sub_f32_e32 v11, v11, v243
	v_sub_f32_e32 v12, v12, v243
	v_sub_f32_e32 v13, v13, v243
	v_sub_f32_e32 v14, v14, v243
	v_sub_f32_e32 v15, v15, v243
	v_pk_mul_f32 v[64:65], v[64:65], v[244:245] op_sel_hi:[1,0]
	v_pk_mul_f32 v[66:67], v[66:67], v[244:245] op_sel_hi:[1,0]
	v_pk_mul_f32 v[68:69], v[68:69], v[244:245] op_sel_hi:[1,0]
	v_pk_mul_f32 v[70:71], v[70:71], v[244:245] op_sel_hi:[1,0]
	v_pk_mul_f32 v[72:73], v[72:73], v[244:245] op_sel_hi:[1,0]
	v_pk_mul_f32 v[74:75], v[74:75], v[244:245] op_sel_hi:[1,0]
	v_pk_mul_f32 v[76:77], v[76:77], v[244:245] op_sel_hi:[1,0]
	v_pk_mul_f32 v[78:79], v[78:79], v[244:245] op_sel_hi:[1,0]
	v_pk_mul_f32 v[48:49], v[48:49], v[244:245] op_sel_hi:[1,0]
	v_pk_mul_f32 v[50:51], v[50:51], v[244:245] op_sel_hi:[1,0]
	v_pk_mul_f32 v[52:53], v[52:53], v[244:245] op_sel_hi:[1,0]
	v_pk_mul_f32 v[54:55], v[54:55], v[244:245] op_sel_hi:[1,0]
	v_pk_mul_f32 v[56:57], v[56:57], v[244:245] op_sel_hi:[1,0]
	v_pk_mul_f32 v[58:59], v[58:59], v[244:245] op_sel_hi:[1,0]
	v_pk_mul_f32 v[60:61], v[60:61], v[244:245] op_sel_hi:[1,0]
	v_pk_mul_f32 v[62:63], v[62:63], v[244:245] op_sel_hi:[1,0]
	v_pk_mul_f32 v[32:33], v[32:33], v[244:245] op_sel_hi:[1,0]
	v_pk_mul_f32 v[34:35], v[34:35], v[244:245] op_sel_hi:[1,0]
	v_pk_mul_f32 v[36:37], v[36:37], v[244:245] op_sel_hi:[1,0]
	v_pk_mul_f32 v[38:39], v[38:39], v[244:245] op_sel_hi:[1,0]
	v_pk_mul_f32 v[40:41], v[40:41], v[244:245] op_sel_hi:[1,0]
	v_pk_mul_f32 v[42:43], v[42:43], v[244:245] op_sel_hi:[1,0]
	v_pk_mul_f32 v[44:45], v[44:45], v[244:245] op_sel_hi:[1,0]
	v_pk_mul_f32 v[46:47], v[46:47], v[244:245] op_sel_hi:[1,0]
	v_pk_mul_f32 v[16:17], v[16:17], v[244:245] op_sel_hi:[1,0]
	v_pk_mul_f32 v[18:19], v[18:19], v[244:245] op_sel_hi:[1,0]
	v_pk_mul_f32 v[20:21], v[20:21], v[244:245] op_sel_hi:[1,0]
	v_pk_mul_f32 v[22:23], v[22:23], v[244:245] op_sel_hi:[1,0]
	v_pk_mul_f32 v[24:25], v[24:25], v[244:245] op_sel_hi:[1,0]
	v_pk_mul_f32 v[26:27], v[26:27], v[244:245] op_sel_hi:[1,0]
	v_pk_mul_f32 v[28:29], v[28:29], v[244:245] op_sel_hi:[1,0]
	v_pk_mul_f32 v[30:31], v[30:31], v[244:245] op_sel_hi:[1,0]
	v_mul_f32_e32 v173, v173, v244
	v_mul_f32_e32 v202, v202, v244
	s_nop 1

; #define LAS __attribute__((address_space(3)))
; template <int MODE> __device__ __forceinline__ void attn_unit(const AttnP& P, int u, LAS char* lds, bool fill) {
;     ...
;     for (int t = 0; t < nt; ++t) {
;         __syncthreads();
; #pragma unroll
;         for (int s = 0; s < NS; ++s) *(LAS u32x4*)(lds + s * ASLOT + lrow * APITCH + lch * 16) = pre[s];
;         __syncthreads();
;         if (t + 1 < nt) ISSUE(t + 1);
;         const int tok0 = TILE_TOK0(t);
;         f32x16 p0, p1;
; #pragma unroll
;         for (int r = 0; r < 16; ++r) { p0[r] = 0.f; p1[r] = 0.f; }
; #pragma unroll
;         for (int ds = 0; ds < 4; ++ds) {
;             const bf16x8 k0 = *(const LAS bf16x8*)(kb + ds * 32);
;             const bf16x8 k1 = *(const LAS bf16x8*)(kb + 32 * APITCH + ds * 32);
;             p0 = __builtin_amdgcn_mfma_f32_32x32x16_bf16(k0, qr[ds], p0, 0, 0, 0);
;             p1 = __builtin_amdgcn_mfma_f32_32x32x16_bf16(k1, qr[ds], p1, 0, 0, 0);
;         }
;         if (MODE == 0) {
;             const bool farl = (tok0 + 63 + 128 <= qtok0), farr = (tok0 - (qtok0 + 31) >= 128) && (tok0 + 64 <= LT);
;             if (farl || farr) { const float cb = farl ? mytab[0] : mytab[256];
; #pragma unroll
;                 for (int r = 0; r < 16; ++r) { p0[r] += cb; p1[r] += cb; } }
;             else {
; #pragma unroll
;                 for (int r = 0; r < 16; ++r) { const int tk0 = tok0 + crow(r, hi), tk1 = tk0 + 32;
;                     int i0 = tk0 - tq + 128; i0 = i0 < 0 ? 0 : (i0 > 256 ? 256 : i0); int i1 = tk1 - tq + 128; i1 = i1 < 0 ? 0 : (i1 > 256 ? 256 : i1);
;                     p0[r] = tk0 < LT ? p0[r] + mytab[i0] : NEGV; p1[r] = tk1 < LT ? p1[r] + mytab[i1] : NEGV; } }
;         } else if (MODE == 2) {
;           if (tok0 >= NMETA && tok0 + 64 <= LT) {
;             const LAS float* t2 = mytab2 + (tok0 - tq + 191 + 4 * hi);
; #pragma unroll
;             for (int r = 0; r < 16; ++r) { p0[r] += t2[(r & 3) + 8 * (r >> 2)]; p1[r] += t2[(r & 3) + 8 * (r >> 2) + 32]; }
;           } else
; #pragma unroll
;             for (int r = 0; r < 16; ++r) { const int tk0 = tok0 + crow(r, hi), tk1 = tk0 + 32; const int r0 = tk0 - tq, r1 = tk1 - tq;
;                 int i0 = r0 + 128; i0 = i0 < 0 ? 0 : (i0 > 256 ? 256 : i0); int i1 = r1 + 128; i1 = i1 < 0 ? 0 : (i1 > 256 ? 256 : i1);
.LBB0_1174:
	v_cmp_lt_f32_e32 vcc, 0xf0000000, v133
	s_cbranch_vccz .Lnat1R_entry
.Lnat1L_entry:
	v_sub_f32_e32 v133, v133, v167
	v_sub_f32_e32 v135, v135, v167
	v_sub_f32_e32 v137, v137, v167
	v_sub_f32_e32 v139, v139, v167
	v_sub_f32_e32 v141, v141, v167
	v_sub_f32_e32 v143, v143, v167
	v_sub_f32_e32 v145, v145, v167
	v_sub_f32_e32 v147, v147, v167
	v_sub_f32_e32 v149, v149, v167
	v_sub_f32_e32 v151, v151, v167
	v_sub_f32_e32 v153, v153, v167
	v_sub_f32_e32 v155, v155, v167
	v_sub_f32_e32 v157, v157, v167
	v_sub_f32_e32 v159, v159, v167
	v_sub_f32_e32 v161, v161, v167
	v_sub_f32_e32 v163, v163, v167
	v_sub_f32_e32 v134, v134, v167
	v_sub_f32_e32 v136, v136, v167
	v_sub_f32_e32 v138, v138, v167
	v_sub_f32_e32 v140, v140, v167
.Lnat1L_loop:
	s_waitcnt lgkmcnt(0)
	s_barrier
	s_waitcnt vmcnt(7)
	ds_write_b128 v165, v[82:85]
	s_waitcnt vmcnt(6)
	ds_write_b128 v165, v[86:89] offset:9216
	s_waitcnt vmcnt(5)
	ds_write_b128 v165, v[90:93] offset:18432
	s_waitcnt vmcnt(4)
	ds_write_b128 v165, v[94:97] offset:27648
	s_waitcnt vmcnt(3)
	ds_write_b128 v165, v[98:101] offset:36864
	s_waitcnt vmcnt(2)
	ds_write_b128 v165, v[102:105] offset:46080
	s_waitcnt vmcnt(1)
	ds_write_b128 v165, v[106:109] offset:55296
	s_waitcnt vmcnt(0)
	ds_write_b128 v165, v[110:113] offset:64512
	s_waitcnt lgkmcnt(0)
	s_barrier
	s_cmpk_eq_i32 s12, 0x1c0
	s_cbranch_scc1 .Lnat1L_noload
	v_add_u32_e32 v34, s12, v115
	v_min_i32_e32 v34, 0x100f, v34
	v_mad_i64_i32 v[34:35], s[14:15], v34, s51, v[126:127]
	v_lshl_add_u64 v[36:37], v[34:35], 0, s[80:81]
	s_mov_b32 s1, s81
	s_mov_b32 s39, s81
	v_lshl_add_u64 v[38:39], v[34:35], 0, s[0:1]
	global_load_dwordx4 v[82:85], v[36:37], off
	global_load_dwordx4 v[86:89], v[38:39], off
	v_lshl_add_u64 v[36:37], v[34:35], 0, s[38:39]
	s_mov_b32 s43, s81
	s_mov_b32 s47, s81
	v_lshl_add_u64 v[38:39], v[34:35], 0, s[42:43]
	global_load_dwordx4 v[90:93], v[36:37], off
	global_load_dwordx4 v[94:97], v[38:39], off
	v_lshl_add_u64 v[36:37], v[34:35], 0, s[46:47]
	s_mov_b32 s49, s81
	s_mov_b32 s59, s81
	v_lshl_add_u64 v[38:39], v[34:35], 0, s[48:49]
	global_load_dwordx4 v[98:101], v[36:37], off
	global_load_dwordx4 v[102:105], v[38:39], off
	v_lshl_add_u64 v[36:37], v[34:35], 0, s[58:59]
	s_mov_b32 s61, s81
	v_lshl_add_u64 v[34:35], v[34:35], 0, s[60:61]
	global_load_dwordx4 v[106:109], v[36:37], off
	global_load_dwordx4 v[110:113], v[34:35], off
.Lnat1L_noload:
	v_mov_b32_e32 v117, s17
	v_cndmask_b32_e64 v117, v117, v116, s[44:45]
	v_lshl_add_u32 v184, v132, 2, v117
	ds_read_b128 v[118:121], v0
	ds_read_b128 v[128:131], v0 offset:4608
	ds_read_b128 v[168:171], v0 offset:32
	ds_read_b128 v[172:175], v0 offset:4640
	ds_read_b128 v[176:179], v0 offset:64
	ds_read_b128 v[180:183], v0 offset:4672
	ds_read2_b32 v[50:51], v184 offset0:0 offset1:1
	ds_read2_b32 v[52:53], v184 offset0:2 offset1:3
	ds_read2_b32 v[54:55], v184 offset0:8 offset1:9
	ds_read2_b32 v[56:57], v184 offset0:10 offset1:11
	ds_read2_b32 v[58:59], v184 offset0:16 offset1:17
	ds_read2_b32 v[60:61], v184 offset0:18 offset1:19
	ds_read2_b32 v[62:63], v184 offset0:24 offset1:25
	ds_read2_b32 v[64:65], v184 offset0:26 offset1:27
	ds_read2_b32 v[34:35], v184 offset0:32 offset1:33
	ds_read2_b32 v[36:37], v184 offset0:34 offset1:35
	s_waitcnt lgkmcnt(9)
	v_add_f32_e32 v50, v50, v133
	v_add_f32_e32 v51, v51, v135
	s_waitcnt lgkmcnt(8)
	v_add_f32_e32 v52, v52, v137
	v_add_f32_e32 v53, v53, v139
	s_waitcnt lgkmcnt(7)
	v_add_f32_e32 v54, v54, v141
	v_add_f32_e32 v55, v55, v143
	s_waitcnt lgkmcnt(6)
	v_add_f32_e32 v56, v56, v145
	v_add_f32_e32 v57, v57, v147
	s_waitcnt lgkmcnt(5)
	v_add_f32_e32 v58, v58, v149
	v_add_f32_e32 v59, v59, v151
	s_waitcnt lgkmcnt(4)
	v_add_f32_e32 v60, v60, v153
	v_add_f32_e32 v61, v61, v155
	s_waitcnt lgkmcnt(3)
	v_add_f32_e32 v62, v62, v157
	v_add_f32_e32 v63, v63, v159
	s_waitcnt lgkmcnt(2)
	v_add_f32_e32 v64, v64, v161
	v_add_f32_e32 v65, v65, v163
	s_waitcnt lgkmcnt(1)
	v_add_f32_e32 v34, v34, v134
	v_add_f32_e32 v35, v35, v136
	s_waitcnt lgkmcnt(0)
	v_add_f32_e32 v36, v36, v138
	v_add_f32_e32 v37, v37, v140
	v_mfma_f32_32x32x16_bf16 v[50:65], v[118:121], v[66:69], v[50:65]
	ds_read_b128 v[118:121], v0 offset:96
	v_mfma_f32_32x32x16_bf16 v[34:49], v[128:131], v[66:69], v[34:49]
	ds_read_b128 v[128:131], v0 offset:4704
	v_mfma_f32_32x32x16_bf16 v[50:65], v[168:171], v[70:73], v[50:65]
	ds_read_b64_tr_b16 v[168:169], v166 offset:9216
	ds_read_b64_tr_b16 v[170:171], v166 offset:10368
	v_mfma_f32_32x32x16_bf16 v[34:49], v[172:175], v[70:73], v[34:49]
	ds_read_b64_tr_b16 v[172:173], v166 offset:9280
	ds_read_b64_tr_b16 v[174:175], v166 offset:10432
	v_mfma_f32_32x32x16_bf16 v[50:65], v[176:179], v[74:77], v[50:65]
	ds_read_b64_tr_b16 v[176:177], v166 offset:11520
	ds_read_b64_tr_b16 v[178:179], v166 offset:12672
	v_mfma_f32_32x32x16_bf16 v[34:49], v[180:183], v[74:77], v[34:49]
	ds_read_b64_tr_b16 v[180:181], v166 offset:11584
	ds_read_b64_tr_b16 v[182:183], v166 offset:12736
	s_waitcnt lgkmcnt(9)
	v_mfma_f32_32x32x16_bf16 v[50:65], v[118:121], v[78:81], v[50:65]
	s_waitcnt lgkmcnt(8)
	v_mfma_f32_32x32x16_bf16 v[34:49], v[128:131], v[78:81], v[34:49]
	ds_read_b64_tr_b16 v[118:119], v166 offset:13824
	ds_read_b64_tr_b16 v[120:121], v166 offset:14976
	ds_read_b64_tr_b16 v[128:129], v166 offset:13888
	ds_read_b64_tr_b16 v[130:131], v166 offset:15040
	s_nop 7
	v_max3_f32 v117, v50, v51, v52
	v_max3_f32 v184, v60, v61, v62
	v_max3_f32 v117, v117, v53, v54
	v_max3_f32 v184, v184, v63, v64
	v_max3_f32 v117, v117, v55, v56
	v_max3_f32 v184, v184, v65, v34
	v_max3_f32 v117, v117, v57, v58
	v_max3_f32 v184, v184, v35, v36
	v_max3_f32 v117, v117, v59, v37
	v_max_f32_e32 v117, v117, v184
	v_mov_b32_e32 v184, v117
	s_nop 1
	v_permlane32_swap_b32_e32 v117, v184
	v_max_f32_e32 v117, v117, v184
	v_cmp_lt_f32_e32 vcc, 0x41000000, v117
	s_cbranch_vccz .Lnat1L_noresc
; #define LAS __attribute__((address_space(3)))
; __device__ __forceinline__ unsigned cvtpk(float lo, float hi) { f32x2_t v = {lo, hi}; bf16x2_t b = __builtin_convertvector(v, bf16x2_t); return __builtin_bit_cast(unsigned, b); }
; __device__ __forceinline__ s16x4 vtr(const LAS char* p) { return __builtin_bit_cast(s16x4, __builtin_amdgcn_ds_read_tr16_b64_v4i16((LAS s16x4*)p)); }
; template <int MODE> __device__ __forceinline__ void attn_unit(const AttnP& P, int u, LAS char* lds, bool fill) {
;     ...
;         if (__any(mx > mrun + 8.0f)) {
;             const float mnew = fmaxf(mrun, mx); const float f = __builtin_amdgcn_exp2f(mrun - mnew); mrun = mnew; lrun *= f;
; #pragma unroll
;             for (int d = 0; d < ND; ++d)
; #pragma unroll
;                 for (int r = 0; r < 16; ++r) o[d][r] *= f;
;         }
;         float sacc = 0.f;
; #pragma unroll
;         for (int r = 0; r < 16; ++r) { p0[r] = __builtin_amdgcn_exp2f(p0[r] - mrun); p1[r] = __builtin_amdgcn_exp2f(p1[r] - mrun); sacc += p0[r] + p1[r]; }
;         lrun += sacc;
;         bf16x8 pf[4];
;         { u32x4 a;
;           a.x = cvtpk(p0[0], p0[1]); a.y = cvtpk(p0[2], p0[3]); a.z = cvtpk(p0[4], p0[5]); a.w = cvtpk(p0[6], p0[7]); pf[0] = __builtin_bit_cast(bf16x8, a);
;           a.x = cvtpk(p0[8], p0[9]); a.y = cvtpk(p0[10], p0[11]); a.z = cvtpk(p0[12], p0[13]); a.w = cvtpk(p0[14], p0[15]); pf[1] = __builtin_bit_cast(bf16x8, a);
;           a.x = cvtpk(p1[0], p1[1]); a.y = cvtpk(p1[2], p1[3]); a.z = cvtpk(p1[4], p1[5]); a.w = cvtpk(p1[6], p1[7]); pf[2] = __builtin_bit_cast(bf16x8, a);
;           a.x = cvtpk(p1[8], p1[9]); a.y = cvtpk(p1[10], p1[11]); a.z = cvtpk(p1[12], p1[13]); a.w = cvtpk(p1[14], p1[15]); pf[3] = __builtin_bit_cast(bf16x8, a); }
; #pragma unroll
;         for (int d = 0; d < ND; ++d) {
;             const int vslot = MODE == 0 ? 2 + (d >> 1) : MODE == 1 ? kslot + 1 : 1;
;             const LAS char* vb = lds + vslot * ASLOT + vrow * APITCH + (d & 1) * 64 + vcolb;
; #pragma unroll
;             for (int ks = 0; ks < 4; ++ks) {
;                 const s16x4 vl = vtr(vb + (16 * ks) * APITCH), vh = vtr(vb + (16 * ks + 8) * APITCH);
;                 const bf16x8 vf = (bf16x8){vl[0], vl[1], vl[2], vl[3], vh[0], vh[1], vh[2], vh[3]};
;                 o[d] = __builtin_amdgcn_mfma_f32_32x32x16_bf16(vf, pf[ks], o[d], 0, 0, 0);
;             }
;         }
	v_max_f32_e32 v117, 0, v117
	v_exp_f32_e64 v184, -v117
	v_add_f32_e32 v167, v167, v117
	v_sub_f32_e32 v133, v133, v117
	v_sub_f32_e32 v135, v135, v117
	v_sub_f32_e32 v137, v137, v117
	v_sub_f32_e32 v139, v139, v117
	v_sub_f32_e32 v141, v141, v117
	v_sub_f32_e32 v143, v143, v117
	v_sub_f32_e32 v145, v145, v117
	v_sub_f32_e32 v147, v147, v117
	v_sub_f32_e32 v149, v149, v117
	v_sub_f32_e32 v151, v151, v117
	v_sub_f32_e32 v153, v153, v117
	v_sub_f32_e32 v155, v155, v117
	v_sub_f32_e32 v157, v157, v117
	v_sub_f32_e32 v159, v159, v117
	v_sub_f32_e32 v161, v161, v117
	v_sub_f32_e32 v163, v163, v117
	v_sub_f32_e32 v134, v134, v117
	v_sub_f32_e32 v136, v136, v117
	v_sub_f32_e32 v138, v138, v117
	v_sub_f32_e32 v140, v140, v117
	v_sub_f32_e32 v50, v50, v117
	v_sub_f32_e32 v51, v51, v117
	v_sub_f32_e32 v52, v52, v117
	v_sub_f32_e32 v53, v53, v117
	v_sub_f32_e32 v54, v54, v117
	v_sub_f32_e32 v55, v55, v117
	v_sub_f32_e32 v56, v56, v117
	v_sub_f32_e32 v57, v57, v117
	v_sub_f32_e32 v58, v58, v117
	v_sub_f32_e32 v59, v59, v117
	v_sub_f32_e32 v60, v60, v117
	v_sub_f32_e32 v61, v61, v117
	v_sub_f32_e32 v62, v62, v117
	v_sub_f32_e32 v63, v63, v117
	v_sub_f32_e32 v64, v64, v117
	v_sub_f32_e32 v65, v65, v117
	v_sub_f32_e32 v34, v34, v117
	v_sub_f32_e32 v35, v35, v117
	v_sub_f32_e32 v36, v36, v117
	v_sub_f32_e32 v37, v37, v117
	v_mul_f32_e32 v2, v2, v184
	v_mul_f32_e32 v3, v3, v184
	v_mul_f32_e32 v4, v4, v184
	v_mul_f32_e32 v5, v5, v184
	v_mul_f32_e32 v6, v6, v184
	v_mul_f32_e32 v7, v7, v184
	v_mul_f32_e32 v8, v8, v184
	v_mul_f32_e32 v9, v9, v184
	v_mul_f32_e32 v10, v10, v184
	v_mul_f32_e32 v11, v11, v184
	v_mul_f32_e32 v12, v12, v184
	v_mul_f32_e32 v13, v13, v184
	v_mul_f32_e32 v14, v14, v184
	v_mul_f32_e32 v15, v15, v184
	v_mul_f32_e32 v16, v16, v184
	v_mul_f32_e32 v17, v17, v184
	v_mul_f32_e32 v18, v18, v184
	v_mul_f32_e32 v19, v19, v184
	v_mul_f32_e32 v20, v20, v184
	v_mul_f32_e32 v21, v21, v184
	v_mul_f32_e32 v22, v22, v184
	v_mul_f32_e32 v23, v23, v184
	v_mul_f32_e32 v24, v24, v184
	v_mul_f32_e32 v25, v25, v184
	v_mul_f32_e32 v26, v26, v184
	v_mul_f32_e32 v27, v27, v184
	v_mul_f32_e32 v28, v28, v184
	v_mul_f32_e32 v29, v29, v184
	v_mul_f32_e32 v30, v30, v184
	v_mul_f32_e32 v31, v31, v184
	v_mul_f32_e32 v32, v32, v184
	v_mul_f32_e32 v33, v33, v184
	v_mul_f32_e32 v114, v114, v184
	s_nop 1
.Lnat1L_noresc:
	v_exp_f32_e32 v50, v50
	v_exp_f32_e32 v51, v51
	v_exp_f32_e32 v52, v52
	v_exp_f32_e32 v53, v53
	v_exp_f32_e32 v54, v54
	v_exp_f32_e32 v55, v55
	v_exp_f32_e32 v56, v56
	v_exp_f32_e32 v57, v57
	v_add_f32_e32 v114, v114, v50
	v_add_f32_e32 v114, v114, v51
	v_add_f32_e32 v114, v114, v52
	v_add_f32_e32 v114, v114, v53
	v_add_f32_e32 v114, v114, v54
	v_add_f32_e32 v114, v114, v55
	v_add_f32_e32 v114, v114, v56
	v_add_f32_e32 v114, v114, v57
	v_cvt_pk_bf16_f32 v50, v50, v51
	v_cvt_pk_bf16_f32 v51, v52, v53
	v_cvt_pk_bf16_f32 v52, v54, v55
	v_cvt_pk_bf16_f32 v53, v56, v57
	s_nop 0
	s_waitcnt lgkmcnt(10)
	v_mfma_f32_32x32x16_bf16 v[2:17], v[168:171], v[50:53], v[2:17]
	s_waitcnt lgkmcnt(8)
	v_mfma_f32_32x32x16_bf16 v[18:33], v[172:175], v[50:53], v[18:33]
	v_exp_f32_e32 v58, v58
	v_exp_f32_e32 v59, v59
	v_exp_f32_e32 v60, v60
	v_exp_f32_e32 v61, v61
	v_exp_f32_e32 v62, v62
	v_exp_f32_e32 v63, v63
	v_exp_f32_e32 v64, v64
	v_exp_f32_e32 v65, v65
	v_add_f32_e32 v114, v114, v58
	v_add_f32_e32 v114, v114, v59
	v_add_f32_e32 v114, v114, v60
	v_add_f32_e32 v114, v114, v61
	v_add_f32_e32 v114, v114, v62
	v_add_f32_e32 v114, v114, v63
	v_add_f32_e32 v114, v114, v64
	v_add_f32_e32 v114, v114, v65
	v_cvt_pk_bf16_f32 v54, v58, v59
	v_cvt_pk_bf16_f32 v55, v60, v61
	v_cvt_pk_bf16_f32 v56, v62, v63
	v_cvt_pk_bf16_f32 v57, v64, v65
	s_nop 0
	s_waitcnt lgkmcnt(6)
	v_mfma_f32_32x32x16_bf16 v[2:17], v[176:179], v[54:57], v[2:17]
	s_waitcnt lgkmcnt(4)
	v_mfma_f32_32x32x16_bf16 v[18:33], v[180:183], v[54:57], v[18:33]
	v_exp_f32_e32 v34, v34
	v_exp_f32_e32 v35, v35
	v_exp_f32_e32 v36, v36
	v_exp_f32_e32 v37, v37
	v_add_f32_e32 v114, v114, v34
	v_add_f32_e32 v114, v114, v35
	v_add_f32_e32 v114, v114, v36
	v_add_f32_e32 v114, v114, v37
	v_cvt_pk_bf16_f32 v58, v34, v35
	v_cvt_pk_bf16_f32 v59, v36, v37
	v_mov_b32_e32 v60, 0
	v_mov_b32_e32 v61, 0
	s_nop 0
	s_waitcnt lgkmcnt(2)
	v_mfma_f32_32x32x16_bf16 v[2:17], v[118:121], v[58:61], v[2:17]
	s_waitcnt lgkmcnt(0)
	v_mfma_f32_32x32x16_bf16 v[18:33], v[128:131], v[58:61], v[18:33]
	s_add_i32 s12, s12, 64
	v_add_u32_e32 v116, 0x7c, v116
	s_cmpk_eq_i32 s12, 0x200
	s_cbranch_scc0 .Lnat1L_loop
	s_branch .LBB0_1178
.Lnat1R_entry:
	v_sub_f32_e32 v157, v157, v167
	v_sub_f32_e32 v159, v159, v167
	v_sub_f32_e32 v161, v161, v167
	v_sub_f32_e32 v163, v163, v167
	v_sub_f32_e32 v134, v134, v167
	v_sub_f32_e32 v136, v136, v167
	v_sub_f32_e32 v138, v138, v167
	v_sub_f32_e32 v140, v140, v167
	v_sub_f32_e32 v142, v142, v167
	v_sub_f32_e32 v144, v144, v167
	v_sub_f32_e32 v146, v146, v167
	v_sub_f32_e32 v148, v148, v167
	v_sub_f32_e32 v150, v150, v167
	v_sub_f32_e32 v152, v152, v167
	v_sub_f32_e32 v154, v154, v167
	v_sub_f32_e32 v156, v156, v167
	v_sub_f32_e32 v158, v158, v167
	v_sub_f32_e32 v160, v160, v167
	v_sub_f32_e32 v162, v162, v167
	v_sub_f32_e32 v164, v164, v167

; template <int MODE> __device__ __forceinline__ void attn_unit(const AttnP& P, int u, LAS char* lds, bool fill) {
;     ...
;         for (int ds = 0; ds < 4; ++ds) {
;             const bf16x8 k0 = *(const LAS bf16x8*)(kb + ds * 32);
;             const bf16x8 k1 = *(const LAS bf16x8*)(kb + 32 * APITCH + ds * 32);
;             p0 = __builtin_amdgcn_mfma_f32_32x32x16_bf16(k0, qr[ds], p0, 0, 0, 0);
;             p1 = __builtin_amdgcn_mfma_f32_32x32x16_bf16(k1, qr[ds], p1, 0, 0, 0);
;         }
;         if (MODE == 0) {
;             const bool farl = (tok0 + 63 + 128 <= qtok0), farr = (tok0 - (qtok0 + 31) >= 128) && (tok0 + 64 <= LT);
;             if (farl || farr) { const float cb = farl ? mytab[0] : mytab[256];
; #pragma unroll
;                 for (int r = 0; r < 16; ++r) { p0[r] += cb; p1[r] += cb; } }
;             else {
; #pragma unroll
;                 for (int r = 0; r < 16; ++r) { const int tk0 = tok0 + crow(r, hi), tk1 = tk0 + 32;
;                     int i0 = tk0 - tq + 128; i0 = i0 < 0 ? 0 : (i0 > 256 ? 256 : i0); int i1 = tk1 - tq + 128; i1 = i1 < 0 ? 0 : (i1 > 256 ? 256 : i1);
;                     p0[r] = tk0 < LT ? p0[r] + mytab[i0] : NEGV; p1[r] = tk1 < LT ? p1[r] + mytab[i1] : NEGV; } }
;         } else if (MODE == 2) {
;           if (tok0 >= NMETA && tok0 + 64 <= LT) {
;             const LAS float* t2 = mytab2 + (tok0 - tq + 191 + 4 * hi);
; #pragma unroll
;             for (int r = 0; r < 16; ++r) { p0[r] += t2[(r & 3) + 8 * (r >> 2)]; p1[r] += t2[(r & 3) + 8 * (r >> 2) + 32]; }
;           } else
; #pragma unroll
;             for (int r = 0; r < 16; ++r) { const int tk0 = tok0 + crow(r, hi), tk1 = tk0 + 32; const int r0 = tk0 - tq, r1 = tk1 - tq;
;                 int i0 = r0 + 128; i0 = i0 < 0 ? 0 : (i0 > 256 ? 256 : i0); int i1 = r1 + 128; i1 = i1 < 0 ? 0 : (i1 > 256 ? 256 : i1);
;                 const bool v0 = (tk0 < NMETA || (r0 >= -128 && r0 <= 128)) && tk0 < LT, v1 = (tk1 < NMETA || (r1 >= -128 && r1 <= 128)) && tk1 < LT;
;                 p0[r] = v0 ? p0[r] + mytab[i0] : NEGV; p1[r] = v1 ? p1[r] + mytab[i1] : NEGV; }
;         } else {
;             if (t == 0) {
; #pragma unroll
;                 for (int r = 0; r < 16; ++r) { const int k0 = crow(r, hi); p0[r] = k0 < NMETA ? p0[r] : NEGV; p1[r] = NEGV; }
;             } else {
;                 const int roff = (rs_ + t - 1) - x2 + 7;
.Lnat1R_noload:
	v_mov_b32_e32 v117, s17
	v_cndmask_b32_e64 v117, v117, v116, s[44:45]
	v_lshl_add_u32 v184, v132, 2, v117
	ds_read_b128 v[118:121], v0
	ds_read_b128 v[128:131], v0 offset:4608
	ds_read_b128 v[168:171], v0 offset:32
	ds_read_b128 v[172:175], v0 offset:4640
	ds_read_b128 v[176:179], v0 offset:64
	ds_read_b128 v[180:183], v0 offset:4672
	ds_read2_b32 v[62:63], v184 offset0:24 offset1:25
	ds_read2_b32 v[64:65], v184 offset0:26 offset1:27
	ds_read2_b32 v[34:35], v184 offset0:32 offset1:33
	ds_read2_b32 v[36:37], v184 offset0:34 offset1:35
	ds_read2_b32 v[38:39], v184 offset0:40 offset1:41
	ds_read2_b32 v[40:41], v184 offset0:42 offset1:43
	ds_read2_b32 v[42:43], v184 offset0:48 offset1:49
	ds_read2_b32 v[44:45], v184 offset0:50 offset1:51
	ds_read2_b32 v[46:47], v184 offset0:56 offset1:57
	ds_read2_b32 v[48:49], v184 offset0:58 offset1:59
	s_waitcnt lgkmcnt(9)
	v_add_f32_e32 v62, v62, v157
	v_add_f32_e32 v63, v63, v159
	s_waitcnt lgkmcnt(8)
	v_add_f32_e32 v64, v64, v161
	v_add_f32_e32 v65, v65, v163
	s_waitcnt lgkmcnt(7)
	v_add_f32_e32 v34, v34, v134
	v_add_f32_e32 v35, v35, v136
	s_waitcnt lgkmcnt(6)
	v_add_f32_e32 v36, v36, v138
	v_add_f32_e32 v37, v37, v140
	s_waitcnt lgkmcnt(5)
	v_add_f32_e32 v38, v38, v142
	v_add_f32_e32 v39, v39, v144
	s_waitcnt lgkmcnt(4)
	v_add_f32_e32 v40, v40, v146
	v_add_f32_e32 v41, v41, v148
	s_waitcnt lgkmcnt(3)
	v_add_f32_e32 v42, v42, v150
	v_add_f32_e32 v43, v43, v152
	s_waitcnt lgkmcnt(2)
	v_add_f32_e32 v44, v44, v154
	v_add_f32_e32 v45, v45, v156
	s_waitcnt lgkmcnt(1)
	v_add_f32_e32 v46, v46, v158
	v_add_f32_e32 v47, v47, v160
	s_waitcnt lgkmcnt(0)
	v_add_f32_e32 v48, v48, v162
	v_add_f32_e32 v49, v49, v164
	v_mfma_f32_32x32x16_bf16 v[50:65], v[118:121], v[66:69], v[50:65]
	ds_read_b128 v[118:121], v0 offset:96
	v_mfma_f32_32x32x16_bf16 v[34:49], v[128:131], v[66:69], v[34:49]
	ds_read_b128 v[128:131], v0 offset:4704
	v_mfma_f32_32x32x16_bf16 v[50:65], v[168:171], v[70:73], v[50:65]
	ds_read_b64_tr_b16 v[168:169], v166 offset:11520
	ds_read_b64_tr_b16 v[170:171], v166 offset:12672
	v_mfma_f32_32x32x16_bf16 v[34:49], v[172:175], v[70:73], v[34:49]
	ds_read_b64_tr_b16 v[172:173], v166 offset:11584
	ds_read_b64_tr_b16 v[174:175], v166 offset:12736
	v_mfma_f32_32x32x16_bf16 v[50:65], v[176:179], v[74:77], v[50:65]
	ds_read_b64_tr_b16 v[176:177], v166 offset:13824
	ds_read_b64_tr_b16 v[178:179], v166 offset:14976
	v_mfma_f32_32x32x16_bf16 v[34:49], v[180:183], v[74:77], v[34:49]
	ds_read_b64_tr_b16 v[180:181], v166 offset:13888
	ds_read_b64_tr_b16 v[182:183], v166 offset:15040
	s_waitcnt lgkmcnt(9)
	v_mfma_f32_32x32x16_bf16 v[50:65], v[118:121], v[78:81], v[50:65]
	s_waitcnt lgkmcnt(8)
	v_mfma_f32_32x32x16_bf16 v[34:49], v[128:131], v[78:81], v[34:49]
	ds_read_b64_tr_b16 v[118:119], v166 offset:16128
	ds_read_b64_tr_b16 v[120:121], v166 offset:17280
	ds_read_b64_tr_b16 v[128:129], v166 offset:16192
	ds_read_b64_tr_b16 v[130:131], v166 offset:17344
	s_nop 7
	v_max3_f32 v117, v62, v63, v64
	v_max3_f32 v184, v40, v41, v42
	v_max3_f32 v117, v117, v65, v34
	v_max3_f32 v184, v184, v43, v44
	v_max3_f32 v117, v117, v35, v36
	v_max3_f32 v184, v184, v45, v46
	v_max3_f32 v117, v117, v37, v38
	v_max3_f32 v184, v184, v47, v48
	v_max3_f32 v117, v117, v39, v49
	v_max_f32_e32 v117, v117, v184
	v_mov_b32_e32 v184, v117
	s_nop 1
	v_permlane32_swap_b32_e32 v117, v184
	v_max_f32_e32 v117, v117, v184
	v_cmp_lt_f32_e32 vcc, 0x41000000, v117
	s_cbranch_vccz .Lnat1R_noresc
	v_max_f32_e32 v117, 0, v117
	v_exp_f32_e64 v184, -v117
	v_add_f32_e32 v167, v167, v117
	v_sub_f32_e32 v157, v157, v117
	v_sub_f32_e32 v159, v159, v117
	v_sub_f32_e32 v161, v161, v117
	v_sub_f32_e32 v163, v163, v117
	v_sub_f32_e32 v134, v134, v117
	v_sub_f32_e32 v136, v136, v117
	v_sub_f32_e32 v138, v138, v117
	v_sub_f32_e32 v140, v140, v117
	v_sub_f32_e32 v142, v142, v117
	v_sub_f32_e32 v144, v144, v117
	v_sub_f32_e32 v146, v146, v117
	v_sub_f32_e32 v148, v148, v117
	v_sub_f32_e32 v150, v150, v117
	v_sub_f32_e32 v152, v152, v117
	v_sub_f32_e32 v154, v154, v117
	v_sub_f32_e32 v156, v156, v117
	v_sub_f32_e32 v158, v158, v117
	v_sub_f32_e32 v160, v160, v117
	v_sub_f32_e32 v162, v162, v117
	v_sub_f32_e32 v164, v164, v117
	v_sub_f32_e32 v62, v62, v117
	v_sub_f32_e32 v63, v63, v117
	v_sub_f32_e32 v64, v64, v117
	v_sub_f32_e32 v65, v65, v117
	v_sub_f32_e32 v34, v34, v117
	v_sub_f32_e32 v35, v35, v117
	v_sub_f32_e32 v36, v36, v117
	v_sub_f32_e32 v37, v37, v117
	v_sub_f32_e32 v38, v38, v117
	v_sub_f32_e32 v39, v39, v117
	v_sub_f32_e32 v40, v40, v117
	v_sub_f32_e32 v41, v41, v117
	v_sub_f32_e32 v42, v42, v117
	v_sub_f32_e32 v43, v43, v117
	v_sub_f32_e32 v44, v44, v117
	v_sub_f32_e32 v45, v45, v117
	v_sub_f32_e32 v46, v46, v117
	v_sub_f32_e32 v47, v47, v117
	v_sub_f32_e32 v48, v48, v117
	v_sub_f32_e32 v49, v49, v117
	v_mul_f32_e32 v2, v2, v184
	v_mul_f32_e32 v3, v3, v184
	v_mul_f32_e32 v4, v4, v184
	v_mul_f32_e32 v5, v5, v184
	v_mul_f32_e32 v6, v6, v184
	v_mul_f32_e32 v7, v7, v184
	v_mul_f32_e32 v8, v8, v184
	v_mul_f32_e32 v9, v9, v184
	v_mul_f32_e32 v10, v10, v184
	v_mul_f32_e32 v11, v11, v184
	v_mul_f32_e32 v12, v12, v184
	v_mul_f32_e32 v13, v13, v184
	v_mul_f32_e32 v14, v14, v184
	v_mul_f32_e32 v15, v15, v184
	v_mul_f32_e32 v16, v16, v184
	v_mul_f32_e32 v17, v17, v184
	v_mul_f32_e32 v18, v18, v184
	v_mul_f32_e32 v19, v19, v184
	v_mul_f32_e32 v20, v20, v184
	v_mul_f32_e32 v21, v21, v184
	v_mul_f32_e32 v22, v22, v184
	v_mul_f32_e32 v23, v23, v184
	v_mul_f32_e32 v24, v24, v184
	v_mul_f32_e32 v25, v25, v184
	v_mul_f32_e32 v26, v26, v184
	v_mul_f32_e32 v27, v27, v184
	v_mul_f32_e32 v28, v28, v184
	v_mul_f32_e32 v29, v29, v184
	v_mul_f32_e32 v30, v30, v184
	v_mul_f32_e32 v31, v31, v184
	v_mul_f32_e32 v32, v32, v184
	v_mul_f32_e32 v33, v33, v184
	v_mul_f32_e32 v114, v114, v184
	s_nop 1
; #define LAS __attribute__((address_space(3)))
; __device__ __forceinline__ unsigned cvtpk(float lo, float hi) { f32x2_t v = {lo, hi}; bf16x2_t b = __builtin_convertvector(v, bf16x2_t); return __builtin_bit_cast(unsigned, b); }
; __device__ __forceinline__ s16x4 vtr(const LAS char* p) { return __builtin_bit_cast(s16x4, __builtin_amdgcn_ds_read_tr16_b64_v4i16((LAS s16x4*)p)); }
; template <int MODE> __device__ __forceinline__ void attn_unit(const AttnP& P, int u, LAS char* lds, bool fill) {
;     ...
;         float sacc = 0.f;
; #pragma unroll
;         for (int r = 0; r < 16; ++r) { p0[r] = __builtin_amdgcn_exp2f(p0[r] - mrun); p1[r] = __builtin_amdgcn_exp2f(p1[r] - mrun); sacc += p0[r] + p1[r]; }
;         lrun += sacc;
;         bf16x8 pf[4];
;         { u32x4 a;
;           a.x = cvtpk(p0[0], p0[1]); a.y = cvtpk(p0[2], p0[3]); a.z = cvtpk(p0[4], p0[5]); a.w = cvtpk(p0[6], p0[7]); pf[0] = __builtin_bit_cast(bf16x8, a);
;           a.x = cvtpk(p0[8], p0[9]); a.y = cvtpk(p0[10], p0[11]); a.z = cvtpk(p0[12], p0[13]); a.w = cvtpk(p0[14], p0[15]); pf[1] = __builtin_bit_cast(bf16x8, a);
;           a.x = cvtpk(p1[0], p1[1]); a.y = cvtpk(p1[2], p1[3]); a.z = cvtpk(p1[4], p1[5]); a.w = cvtpk(p1[6], p1[7]); pf[2] = __builtin_bit_cast(bf16x8, a);
;           a.x = cvtpk(p1[8], p1[9]); a.y = cvtpk(p1[10], p1[11]); a.z = cvtpk(p1[12], p1[13]); a.w = cvtpk(p1[14], p1[15]); pf[3] = __builtin_bit_cast(bf16x8, a); }
; #pragma unroll
;         for (int d = 0; d < ND; ++d) {
;             const int vslot = MODE == 0 ? 2 + (d >> 1) : MODE == 1 ? kslot + 1 : 1;
;             const LAS char* vb = lds + vslot * ASLOT + vrow * APITCH + (d & 1) * 64 + vcolb;
; #pragma unroll
;             for (int ks = 0; ks < 4; ++ks) {
;                 const s16x4 vl = vtr(vb + (16 * ks) * APITCH), vh = vtr(vb + (16 * ks + 8) * APITCH);
;                 const bf16x8 vf = (bf16x8){vl[0], vl[1], vl[2], vl[3], vh[0], vh[1], vh[2], vh[3]};
;                 o[d] = __builtin_amdgcn_mfma_f32_32x32x16_bf16(vf, pf[ks], o[d], 0, 0, 0);
;             }
;         }
.Lnat1R_noresc:
	v_exp_f32_e32 v62, v62
	v_exp_f32_e32 v63, v63
	v_exp_f32_e32 v64, v64
	v_exp_f32_e32 v65, v65
	v_add_f32_e32 v114, v114, v62
	v_add_f32_e32 v114, v114, v63
	v_add_f32_e32 v114, v114, v64
	v_add_f32_e32 v114, v114, v65
	v_mov_b32_e32 v54, 0
	v_mov_b32_e32 v55, 0
	v_cvt_pk_bf16_f32 v56, v62, v63
	v_cvt_pk_bf16_f32 v57, v64, v65
	s_nop 0
	s_waitcnt lgkmcnt(10)
	v_mfma_f32_32x32x16_bf16 v[2:17], v[168:171], v[54:57], v[2:17]
	s_waitcnt lgkmcnt(8)
	v_mfma_f32_32x32x16_bf16 v[18:33], v[172:175], v[54:57], v[18:33]
	v_exp_f32_e32 v34, v34
	v_exp_f32_e32 v35, v35
	v_exp_f32_e32 v36, v36
	v_exp_f32_e32 v37, v37
	v_exp_f32_e32 v38, v38
	v_exp_f32_e32 v39, v39
	v_exp_f32_e32 v40, v40
	v_exp_f32_e32 v41, v41
	v_add_f32_e32 v114, v114, v34
	v_add_f32_e32 v114, v114, v35
	v_add_f32_e32 v114, v114, v36
	v_add_f32_e32 v114, v114, v37
	v_add_f32_e32 v114, v114, v38
	v_add_f32_e32 v114, v114, v39
	v_add_f32_e32 v114, v114, v40
	v_add_f32_e32 v114, v114, v41
	v_cvt_pk_bf16_f32 v58, v34, v35
	v_cvt_pk_bf16_f32 v59, v36, v37
	v_cvt_pk_bf16_f32 v60, v38, v39
	v_cvt_pk_bf16_f32 v61, v40, v41
	s_nop 0
	s_waitcnt lgkmcnt(6)
	v_mfma_f32_32x32x16_bf16 v[2:17], v[176:179], v[58:61], v[2:17]
	s_waitcnt lgkmcnt(4)
	v_mfma_f32_32x32x16_bf16 v[18:33], v[180:183], v[58:61], v[18:33]
	v_exp_f32_e32 v42, v42
	v_exp_f32_e32 v43, v43
	v_exp_f32_e32 v44, v44
	v_exp_f32_e32 v45, v45
	v_exp_f32_e32 v46, v46
	v_exp_f32_e32 v47, v47
	v_exp_f32_e32 v48, v48
	v_exp_f32_e32 v49, v49
	v_add_f32_e32 v114, v114, v42
	v_add_f32_e32 v114, v114, v43
	v_add_f32_e32 v114, v114, v44
	v_add_f32_e32 v114, v114, v45
	v_add_f32_e32 v114, v114, v46
	v_add_f32_e32 v114, v114, v47
	v_add_f32_e32 v114, v114, v48
	v_add_f32_e32 v114, v114, v49
	v_cvt_pk_bf16_f32 v62, v42, v43
	v_cvt_pk_bf16_f32 v63, v44, v45
	v_cvt_pk_bf16_f32 v64, v46, v47
	v_cvt_pk_bf16_f32 v65, v48, v49
	s_nop 0
	s_waitcnt lgkmcnt(2)
	v_mfma_f32_32x32x16_bf16 v[2:17], v[118:121], v[62:65], v[2:17]
	s_waitcnt lgkmcnt(0)
	v_mfma_f32_32x32x16_bf16 v[18:33], v[128:131], v[62:65], v[18:33]
	s_add_i32 s12, s12, 64
	v_add_u32_e32 v116, 0x7c, v116
	s_cmpk_eq_i32 s12, 0x200
	s_cbranch_scc0 .Lnat1R_loop
	s_branch .LBB0_1178

; #define LAS __attribute__((address_space(3)))
; __device__ __forceinline__ int crow(int r, int hi) { return (r & 3) + 8 * (r >> 2) + 4 * hi; }
; #define ISSUE(t) do { int tok_ = TILE_TOK0(t) + lrow; tok_ = tok_ > LT - 1 ? LT - 1 : tok_; const bf16_t* src_ = pb + (size_t)tok_ * INC; \
;         _Pragma("unroll") for (int s = 0; s < NS; ++s) pre[s] = *(const u32x4*)(src_ + STREAM_COL(s)); } while (0)
; template <int MODE> __device__ __forceinline__ void attn_unit(const AttnP& P, int u, LAS char* lds, bool fill) {
;     ...
;     const int lrow = tid >> 3, lch = tid & 7;
;     u32x4 pre[NS];
;     const bf16_t* pb = P.proj + (size_t)b * LT * INC + lch * 8;
;     ...
;     ISSUE(0);
;     int ccol = 0, cstart = 0;
;     if (MODE == 1 && !metaunit) { ccol = (tq - NMETA) & 63; cstart = ccol - 8; cstart = cstart < 0 ? 0 : (cstart > 48 ? 48 : cstart); }
;     float ng0[16], ng1[16];
;     if (MODE == 1) {
; #pragma unroll
;         for (int r = 0; r < 16; ++r) { const int k0 = crow(r, hi), k1 = k0 + 32; ng0[r] = (k0 >= cstart && k0 < cstart + 16) ? 0.f : NEGV; ng1[r] = (k1 >= cstart && k1 < cstart + 16) ? 0.f : NEGV; }
;     }
;     const LAS char* kb = lds + kslot * ASLOT + r32 * APITCH + hi * 16;
;     const int vrow = 4 * hi + ((lane & 15) >> 2), vcolb = 32 * ((lane >> 4) & 1) + 8 * (lane & 3);
;     for (int t = 0; t < nt; ++t) {
;         __syncthreads();
; #pragma unroll
;         for (int s = 0; s < NS; ++s) *(LAS u32x4*)(lds + s * ASLOT + lrow * APITCH + lch * 16) = pre[s];
;         __syncthreads();
;         if (t + 1 < nt) ISSUE(t + 1);
.Lnat2L_entry:
	v_sub_f32_e32 v133, v133, v167
	v_sub_f32_e32 v135, v135, v167
	v_sub_f32_e32 v137, v137, v167
	v_sub_f32_e32 v139, v139, v167
	v_sub_f32_e32 v141, v141, v167
	v_sub_f32_e32 v143, v143, v167
	v_sub_f32_e32 v145, v145, v167
	v_sub_f32_e32 v147, v147, v167
	v_sub_f32_e32 v149, v149, v167
	v_sub_f32_e32 v151, v151, v167
	v_sub_f32_e32 v153, v153, v167
	v_sub_f32_e32 v155, v155, v167
	v_sub_f32_e32 v157, v157, v167
	v_sub_f32_e32 v159, v159, v167
	v_sub_f32_e32 v161, v161, v167
	v_sub_f32_e32 v163, v163, v167
	v_sub_f32_e32 v134, v134, v167
	v_sub_f32_e32 v136, v136, v167
	v_sub_f32_e32 v138, v138, v167
	v_sub_f32_e32 v140, v140, v167
.Lnat2L_loop:
	s_waitcnt lgkmcnt(0)
	s_barrier
	s_waitcnt vmcnt(7)
	ds_write_b128 v165, v[82:85]
	s_waitcnt vmcnt(6)
	ds_write_b128 v165, v[86:89] offset:9216
	s_waitcnt vmcnt(5)
	ds_write_b128 v165, v[90:93] offset:18432
	s_waitcnt vmcnt(4)
	ds_write_b128 v165, v[94:97] offset:27648
	s_waitcnt vmcnt(3)
	ds_write_b128 v165, v[98:101] offset:36864
	s_waitcnt vmcnt(2)
	ds_write_b128 v165, v[102:105] offset:46080
	s_waitcnt vmcnt(1)
	ds_write_b128 v165, v[106:109] offset:55296
	s_waitcnt vmcnt(0)
	ds_write_b128 v165, v[110:113] offset:64512
	s_waitcnt lgkmcnt(0)
	s_barrier
	s_cmpk_eq_i32 s13, 0x1c0
	s_cbranch_scc1 .Lnat2L_noload
	v_add_u32_e32 v34, s13, v115
	v_min_i32_e32 v34, 0x100f, v34
	v_mad_i64_i32 v[34:35], s[14:15], v34, s51, v[126:127]
	v_lshl_add_u64 v[36:37], s[42:43], 1, v[34:35]
	v_lshl_add_u64 v[38:39], s[58:59], 1, v[34:35]
	global_load_dwordx4 v[82:85], v[36:37], off
	global_load_dwordx4 v[86:89], v[38:39], off
	v_lshl_add_u64 v[36:37], s[60:61], 1, v[34:35]
	v_lshl_add_u64 v[38:39], s[62:63], 1, v[34:35]
	global_load_dwordx4 v[90:93], v[36:37], off
	global_load_dwordx4 v[94:97], v[38:39], off
	v_lshl_add_u64 v[36:37], s[64:65], 1, v[34:35]
	v_lshl_add_u64 v[38:39], s[66:67], 1, v[34:35]
	global_load_dwordx4 v[98:101], v[36:37], off
	global_load_dwordx4 v[102:105], v[38:39], off
	v_lshl_add_u64 v[36:37], s[38:39], 1, v[34:35]
	v_lshl_add_u64 v[34:35], s[0:1], 1, v[34:35]
	global_load_dwordx4 v[106:109], v[36:37], off
	global_load_dwordx4 v[110:113], v[34:35], off

; #define LAS __attribute__((address_space(3)))
; __device__ __forceinline__ unsigned cvtpk(float lo, float hi) { f32x2_t v = {lo, hi}; bf16x2_t b = __builtin_convertvector(v, bf16x2_t); return __builtin_bit_cast(unsigned, b); }
; __device__ __forceinline__ s16x4 vtr(const LAS char* p) { return __builtin_bit_cast(s16x4, __builtin_amdgcn_ds_read_tr16_b64_v4i16((LAS s16x4*)p)); }
; template <int MODE> __device__ __forceinline__ void attn_unit(const AttnP& P, int u, LAS char* lds, bool fill) {
;     ...
;         float sacc = 0.f;
; #pragma unroll
;         for (int r = 0; r < 16; ++r) { p0[r] = __builtin_amdgcn_exp2f(p0[r] - mrun); p1[r] = __builtin_amdgcn_exp2f(p1[r] - mrun); sacc += p0[r] + p1[r]; }
;         lrun += sacc;
;         bf16x8 pf[4];
;         { u32x4 a;
;           a.x = cvtpk(p0[0], p0[1]); a.y = cvtpk(p0[2], p0[3]); a.z = cvtpk(p0[4], p0[5]); a.w = cvtpk(p0[6], p0[7]); pf[0] = __builtin_bit_cast(bf16x8, a);
;           a.x = cvtpk(p0[8], p0[9]); a.y = cvtpk(p0[10], p0[11]); a.z = cvtpk(p0[12], p0[13]); a.w = cvtpk(p0[14], p0[15]); pf[1] = __builtin_bit_cast(bf16x8, a);
;           a.x = cvtpk(p1[0], p1[1]); a.y = cvtpk(p1[2], p1[3]); a.z = cvtpk(p1[4], p1[5]); a.w = cvtpk(p1[6], p1[7]); pf[2] = __builtin_bit_cast(bf16x8, a);
;           a.x = cvtpk(p1[8], p1[9]); a.y = cvtpk(p1[10], p1[11]); a.z = cvtpk(p1[12], p1[13]); a.w = cvtpk(p1[14], p1[15]); pf[3] = __builtin_bit_cast(bf16x8, a); }
; #pragma unroll
;         for (int d = 0; d < ND; ++d) {
;             const int vslot = MODE == 0 ? 2 + (d >> 1) : MODE == 1 ? kslot + 1 : 1;
;             const LAS char* vb = lds + vslot * ASLOT + vrow * APITCH + (d & 1) * 64 + vcolb;
; #pragma unroll
;             for (int ks = 0; ks < 4; ++ks) {
;                 const s16x4 vl = vtr(vb + (16 * ks) * APITCH), vh = vtr(vb + (16 * ks + 8) * APITCH);
;                 const bf16x8 vf = (bf16x8){vl[0], vl[1], vl[2], vl[3], vh[0], vh[1], vh[2], vh[3]};
;                 o[d] = __builtin_amdgcn_mfma_f32_32x32x16_bf16(vf, pf[ks], o[d], 0, 0, 0);
;             }
;         }
.Lnat2L_noresc:
	v_exp_f32_e32 v50, v50
	v_exp_f32_e32 v51, v51
	v_exp_f32_e32 v52, v52
	v_exp_f32_e32 v53, v53
	v_exp_f32_e32 v54, v54
	v_exp_f32_e32 v55, v55
	v_exp_f32_e32 v56, v56
	v_exp_f32_e32 v57, v57
	v_add_f32_e32 v114, v114, v50
	v_add_f32_e32 v114, v114, v51
	v_add_f32_e32 v114, v114, v52
	v_add_f32_e32 v114, v114, v53
	v_add_f32_e32 v114, v114, v54
	v_add_f32_e32 v114, v114, v55
	v_add_f32_e32 v114, v114, v56
	v_add_f32_e32 v114, v114, v57
	v_cvt_pk_bf16_f32 v50, v50, v51
	v_cvt_pk_bf16_f32 v51, v52, v53
	v_cvt_pk_bf16_f32 v52, v54, v55
	v_cvt_pk_bf16_f32 v53, v56, v57
	s_nop 0
	s_waitcnt lgkmcnt(10)
	v_mfma_f32_32x32x16_bf16 v[2:17], v[168:171], v[50:53], v[2:17]
	s_waitcnt lgkmcnt(8)
	v_mfma_f32_32x32x16_bf16 v[18:33], v[172:175], v[50:53], v[18:33]
	v_exp_f32_e32 v58, v58
	v_exp_f32_e32 v59, v59
	v_exp_f32_e32 v60, v60
	v_exp_f32_e32 v61, v61
	v_exp_f32_e32 v62, v62
	v_exp_f32_e32 v63, v63
	v_exp_f32_e32 v64, v64
	v_exp_f32_e32 v65, v65
	v_add_f32_e32 v114, v114, v58
	v_add_f32_e32 v114, v114, v59
	v_add_f32_e32 v114, v114, v60
	v_add_f32_e32 v114, v114, v61
	v_add_f32_e32 v114, v114, v62
	v_add_f32_e32 v114, v114, v63
	v_add_f32_e32 v114, v114, v64
	v_add_f32_e32 v114, v114, v65
	v_cvt_pk_bf16_f32 v54, v58, v59
	v_cvt_pk_bf16_f32 v55, v60, v61
	v_cvt_pk_bf16_f32 v56, v62, v63
	v_cvt_pk_bf16_f32 v57, v64, v65
	s_nop 0
	s_waitcnt lgkmcnt(6)
	v_mfma_f32_32x32x16_bf16 v[2:17], v[176:179], v[54:57], v[2:17]
	s_waitcnt lgkmcnt(4)
	v_mfma_f32_32x32x16_bf16 v[18:33], v[180:183], v[54:57], v[18:33]
	v_exp_f32_e32 v34, v34
	v_exp_f32_e32 v35, v35
	v_exp_f32_e32 v36, v36
	v_exp_f32_e32 v37, v37
	v_add_f32_e32 v114, v114, v34
	v_add_f32_e32 v114, v114, v35
	v_add_f32_e32 v114, v114, v36
	v_add_f32_e32 v114, v114, v37
	v_cvt_pk_bf16_f32 v58, v34, v35
	v_cvt_pk_bf16_f32 v59, v36, v37
	v_mov_b32_e32 v60, 0
	v_mov_b32_e32 v61, 0
	s_nop 0
	s_waitcnt lgkmcnt(2)
	v_mfma_f32_32x32x16_bf16 v[2:17], v[118:121], v[58:61], v[2:17]
	s_waitcnt lgkmcnt(0)
	v_mfma_f32_32x32x16_bf16 v[18:33], v[128:131], v[58:61], v[18:33]
	s_add_i32 s13, s13, 64
	v_add_u32_e32 v116, 0x7c, v116
	s_cmpk_eq_i32 s13, 0x200
	s_cbranch_scc0 .Lnat2L_loop
	s_branch .LBB0_1365

; #define LAS __attribute__((address_space(3)))
; __device__ __forceinline__ unsigned cvtpk(float lo, float hi) { f32x2_t v = {lo, hi}; bf16x2_t b = __builtin_convertvector(v, bf16x2_t); return __builtin_bit_cast(unsigned, b); }
; __device__ __forceinline__ s16x4 vtr(const LAS char* p) { return __builtin_bit_cast(s16x4, __builtin_amdgcn_ds_read_tr16_b64_v4i16((LAS s16x4*)p)); }
; template <int MODE> __device__ __forceinline__ void attn_unit(const AttnP& P, int u, LAS char* lds, bool fill) {
;     ...
;         float sacc = 0.f;
; #pragma unroll
;         for (int r = 0; r < 16; ++r) { p0[r] = __builtin_amdgcn_exp2f(p0[r] - mrun); p1[r] = __builtin_amdgcn_exp2f(p1[r] - mrun); sacc += p0[r] + p1[r]; }
;         lrun += sacc;
;         bf16x8 pf[4];
;         { u32x4 a;
;           a.x = cvtpk(p0[0], p0[1]); a.y = cvtpk(p0[2], p0[3]); a.z = cvtpk(p0[4], p0[5]); a.w = cvtpk(p0[6], p0[7]); pf[0] = __builtin_bit_cast(bf16x8, a);
;           a.x = cvtpk(p0[8], p0[9]); a.y = cvtpk(p0[10], p0[11]); a.z = cvtpk(p0[12], p0[13]); a.w = cvtpk(p0[14], p0[15]); pf[1] = __builtin_bit_cast(bf16x8, a);
;           a.x = cvtpk(p1[0], p1[1]); a.y = cvtpk(p1[2], p1[3]); a.z = cvtpk(p1[4], p1[5]); a.w = cvtpk(p1[6], p1[7]); pf[2] = __builtin_bit_cast(bf16x8, a);
;           a.x = cvtpk(p1[8], p1[9]); a.y = cvtpk(p1[10], p1[11]); a.z = cvtpk(p1[12], p1[13]); a.w = cvtpk(p1[14], p1[15]); pf[3] = __builtin_bit_cast(bf16x8, a); }
; #pragma unroll
;         for (int d = 0; d < ND; ++d) {
;             const int vslot = MODE == 0 ? 2 + (d >> 1) : MODE == 1 ? kslot + 1 : 1;
;             const LAS char* vb = lds + vslot * ASLOT + vrow * APITCH + (d & 1) * 64 + vcolb;
; #pragma unroll
;             for (int ks = 0; ks < 4; ++ks) {
;                 const s16x4 vl = vtr(vb + (16 * ks) * APITCH), vh = vtr(vb + (16 * ks + 8) * APITCH);
;                 const bf16x8 vf = (bf16x8){vl[0], vl[1], vl[2], vl[3], vh[0], vh[1], vh[2], vh[3]};
;                 o[d] = __builtin_amdgcn_mfma_f32_32x32x16_bf16(vf, pf[ks], o[d], 0, 0, 0);
;             }
;         }
.Lnat2R_noresc:
	v_exp_f32_e32 v62, v62
	v_exp_f32_e32 v63, v63
	v_exp_f32_e32 v64, v64
	v_exp_f32_e32 v65, v65
	v_add_f32_e32 v114, v114, v62
	v_add_f32_e32 v114, v114, v63
	v_add_f32_e32 v114, v114, v64
	v_add_f32_e32 v114, v114, v65
	v_mov_b32_e32 v54, 0
	v_mov_b32_e32 v55, 0
	v_cvt_pk_bf16_f32 v56, v62, v63
	v_cvt_pk_bf16_f32 v57, v64, v65
	s_nop 0
	s_waitcnt lgkmcnt(10)
	v_mfma_f32_32x32x16_bf16 v[2:17], v[168:171], v[54:57], v[2:17]
	s_waitcnt lgkmcnt(8)
	v_mfma_f32_32x32x16_bf16 v[18:33], v[172:175], v[54:57], v[18:33]
	v_exp_f32_e32 v34, v34
	v_exp_f32_e32 v35, v35
	v_exp_f32_e32 v36, v36
	v_exp_f32_e32 v37, v37
	v_exp_f32_e32 v38, v38
	v_exp_f32_e32 v39, v39
	v_exp_f32_e32 v40, v40
	v_exp_f32_e32 v41, v41
	v_add_f32_e32 v114, v114, v34
	v_add_f32_e32 v114, v114, v35
	v_add_f32_e32 v114, v114, v36
	v_add_f32_e32 v114, v114, v37
	v_add_f32_e32 v114, v114, v38
	v_add_f32_e32 v114, v114, v39
	v_add_f32_e32 v114, v114, v40
	v_add_f32_e32 v114, v114, v41
	v_cvt_pk_bf16_f32 v58, v34, v35
	v_cvt_pk_bf16_f32 v59, v36, v37
	v_cvt_pk_bf16_f32 v60, v38, v39
	v_cvt_pk_bf16_f32 v61, v40, v41
	s_nop 0
	s_waitcnt lgkmcnt(6)
	v_mfma_f32_32x32x16_bf16 v[2:17], v[176:179], v[58:61], v[2:17]
	s_waitcnt lgkmcnt(4)
	v_mfma_f32_32x32x16_bf16 v[18:33], v[180:183], v[58:61], v[18:33]
	v_exp_f32_e32 v42, v42
	v_exp_f32_e32 v43, v43
	v_exp_f32_e32 v44, v44
	v_exp_f32_e32 v45, v45
	v_exp_f32_e32 v46, v46
	v_exp_f32_e32 v47, v47
	v_exp_f32_e32 v48, v48
	v_exp_f32_e32 v49, v49
	v_add_f32_e32 v114, v114, v42
	v_add_f32_e32 v114, v114, v43
	v_add_f32_e32 v114, v114, v44
	v_add_f32_e32 v114, v114, v45
	v_add_f32_e32 v114, v114, v46
	v_add_f32_e32 v114, v114, v47
	v_add_f32_e32 v114, v114, v48
	v_add_f32_e32 v114, v114, v49
	v_cvt_pk_bf16_f32 v62, v42, v43
	v_cvt_pk_bf16_f32 v63, v44, v45
	v_cvt_pk_bf16_f32 v64, v46, v47
	v_cvt_pk_bf16_f32 v65, v48, v49
	s_nop 0
	s_waitcnt lgkmcnt(2)
	v_mfma_f32_32x32x16_bf16 v[2:17], v[118:121], v[62:65], v[2:17]
	s_waitcnt lgkmcnt(0)
	v_mfma_f32_32x32x16_bf16 v[18:33], v[128:131], v[62:65], v[18:33]
	s_add_i32 s13, s13, 64
	v_add_u32_e32 v116, 0x7c, v116
	s_cmpk_eq_i32 s13, 0x200
	s_cbranch_scc0 .Lnat2R_loop
	s_branch .LBB0_1365
